# GEMM K-loops: first iteration of each unit peeled with SrcC=0, accumulator reset removed
# baseline (speedup 1.0000x reference)
.LBB0_162:
	s_ashr_i32 s39, s38, 31
	s_lshl_b64 s[40:41], s[38:39], 19
	s_add_u32 s40, s74, s40
	s_addc_u32 s41, s75, s41
	s_and_b64 s[42:43], s[0:1], exec
	s_cselect_b32 s5, s41, s9
	s_cselect_b32 s7, s40, s8
	s_ashr_i32 s37, s36, 31
	s_lshl_b64 s[42:43], s[36:37], 19
	s_add_u32 s42, s16, s42
	s_addc_u32 s43, s17, s43
	s_and_b64 s[46:47], s[0:1], exec
	s_cselect_b32 s37, s43, s45
	s_cselect_b32 s39, s42, s44
	s_add_u32 s8, s8, 0x40080
	s_addc_u32 s9, s9, 0
	s_add_u32 s48, s44, 0x100
	s_addc_u32 s49, s45, 0
	s_mov_b32 s50, -2
	ds_read_b128 v[148:151], v155
	ds_read_b128 v[160:163], v155 offset:1024
	ds_read_b128 v[164:167], v155 offset:2048
	ds_read_b128 v[168:171], v155 offset:3072
	ds_read_b128 v[172:175], v156
	ds_read_b128 v[176:179], v156 offset:1024
	ds_read_b128 v[180:183], v156 offset:2048
	ds_read_b128 v[184:187], v156 offset:3072
	s_add_u32 s44, s8, 0xfffc0080
	s_addc_u32 s45, s9, -1
	s_cmp_eq_u32 s50, 12
	s_cselect_b32 s47, s5, s45
	s_cselect_b32 s46, s7, s44
	s_cselect_b32 s45, s37, s49
	s_cselect_b32 s44, s39, s48
	v_lshl_add_u64 v[222:223], s[8:9], 0, v[138:139]
	s_add_i32 m0, s20, 0xc000
	ds_read_b128 v[188:191], v157
	ds_read_b128 v[194:197], v157 offset:1024
	ds_read_b128 v[198:201], v157 offset:2048
	ds_read_b128 v[202:205], v157 offset:3072
	ds_read_b128 v[206:209], v157 offset:4096
	ds_read_b128 v[210:213], v157 offset:5120
	ds_read_b128 v[214:217], v157 offset:6144
	ds_read_b128 v[218:221], v157 offset:7168
	global_load_lds_dwordx4 v[222:223], off
	v_lshl_add_u64 v[222:223], s[8:9], 0, v[140:141]
	s_add_i32 m0, s20, 0xe000
	s_nop 0
	global_load_lds_dwordx4 v[222:223], off
	s_waitcnt vmcnt(8)
	s_waitcnt lgkmcnt(0)
	s_barrier
	s_waitcnt lgkmcnt(0)
	v_mfma_f32_16x16x32_bf16 v[124:127], v[148:151], v[188:191], 0
	v_mfma_f32_16x16x32_bf16 v[120:123], v[164:167], v[188:191], 0
	v_mfma_f32_16x16x32_bf16 v[108:111], v[148:151], v[198:201], 0
	v_mfma_f32_16x16x32_bf16 v[104:107], v[164:167], v[198:201], 0
	v_mfma_f32_16x16x32_bf16 v[96:99], v[148:151], v[206:209], 0
	v_mfma_f32_16x16x32_bf16 v[88:91], v[164:167], v[206:209], 0
	v_mfma_f32_16x16x32_bf16 v[84:87], v[148:151], v[214:217], 0
	v_mfma_f32_16x16x32_bf16 v[76:79], v[164:167], v[214:217], 0
	v_mfma_f32_16x16x32_bf16 v[124:127], v[160:163], v[194:197], v[124:127]
	v_mfma_f32_16x16x32_bf16 v[120:123], v[168:171], v[194:197], v[120:123]
	v_mfma_f32_16x16x32_bf16 v[108:111], v[160:163], v[202:205], v[108:111]
	v_mfma_f32_16x16x32_bf16 v[104:107], v[168:171], v[202:205], v[104:107]
	v_mfma_f32_16x16x32_bf16 v[96:99], v[160:163], v[210:213], v[96:99]
	v_mfma_f32_16x16x32_bf16 v[88:91], v[168:171], v[210:213], v[88:91]
	v_mfma_f32_16x16x32_bf16 v[84:87], v[160:163], v[218:221], v[84:87]
	v_mfma_f32_16x16x32_bf16 v[76:79], v[168:171], v[218:221], v[76:79]
	v_mfma_f32_16x16x32_bf16 v[116:119], v[172:175], v[188:191], 0
	v_mfma_f32_16x16x32_bf16 v[112:115], v[180:183], v[188:191], 0
	v_mfma_f32_16x16x32_bf16 v[100:103], v[172:175], v[198:201], 0
	v_mfma_f32_16x16x32_bf16 v[92:95], v[180:183], v[198:201], 0
	v_mfma_f32_16x16x32_bf16 v[80:83], v[172:175], v[206:209], 0
	v_mfma_f32_16x16x32_bf16 v[72:75], v[180:183], v[206:209], 0
	v_mfma_f32_16x16x32_bf16 v[68:71], v[172:175], v[214:217], 0
	v_mfma_f32_16x16x32_bf16 v[64:67], v[180:183], v[214:217], 0
	v_mfma_f32_16x16x32_bf16 v[116:119], v[176:179], v[194:197], v[116:119]
	v_mfma_f32_16x16x32_bf16 v[112:115], v[184:187], v[194:197], v[112:115]
	v_mfma_f32_16x16x32_bf16 v[100:103], v[176:179], v[202:205], v[100:103]
	v_mfma_f32_16x16x32_bf16 v[92:95], v[184:187], v[202:205], v[92:95]
	v_mfma_f32_16x16x32_bf16 v[80:83], v[176:179], v[210:213], v[80:83]
	v_mfma_f32_16x16x32_bf16 v[72:75], v[184:187], v[210:213], v[72:75]
	v_mfma_f32_16x16x32_bf16 v[68:71], v[176:179], v[218:221], v[68:71]
	v_mfma_f32_16x16x32_bf16 v[64:67], v[184:187], v[218:221], v[64:67]
	s_barrier
	s_add_i32 s51, s72, s15
	v_lshl_add_u64 v[222:223], s[44:45], 0, v[130:131]
	s_mov_b32 m0, s51
	ds_read_b128 v[188:191], v157 offset:16384
	ds_read_b128 v[194:197], v157 offset:17408
	ds_read_b128 v[198:201], v157 offset:18432
	ds_read_b128 v[202:205], v157 offset:19456
	ds_read_b128 v[206:209], v157 offset:20480
	ds_read_b128 v[210:213], v157 offset:21504
	ds_read_b128 v[214:217], v157 offset:22528
	ds_read_b128 v[218:221], v157 offset:23552
	global_load_lds_dwordx4 v[222:223], off
	s_add_i32 m0, s51, 0x2000
	s_add_u32 s64, s44, 0x40000
	v_lshl_add_u64 v[224:225], s[44:45], 0, v[134:135]
	s_addc_u32 s65, s45, 0
	s_add_i32 s51, s73, s15
	global_load_lds_dwordx4 v[224:225], off
	v_lshl_add_u64 v[226:227], s[64:65], 0, v[130:131]
	s_mov_b32 m0, s51
	v_lshl_add_u64 v[228:229], s[46:47], 0, v[132:133]
	global_load_lds_dwordx4 v[226:227], off
	v_lshl_add_u64 v[226:227], s[64:65], 0, v[134:135]
	s_add_i32 m0, s51, 0x2000
	s_nop 0
	global_load_lds_dwordx4 v[226:227], off
	v_lshl_add_u64 v[226:227], s[46:47], 0, v[128:129]
	s_mov_b32 m0, s20
	s_nop 0
	global_load_lds_dwordx4 v[226:227], off
	s_mov_b32 m0, s21
	s_nop 0
	global_load_lds_dwordx4 v[228:229], off
	s_waitcnt vmcnt(8)
	s_waitcnt lgkmcnt(0)
	s_barrier
	s_waitcnt lgkmcnt(0)
	v_mfma_f32_16x16x32_bf16 v[60:63], v[148:151], v[188:191], 0
	v_mfma_f32_16x16x32_bf16 v[56:59], v[164:167], v[188:191], 0
	v_mfma_f32_16x16x32_bf16 v[44:47], v[148:151], v[198:201], 0
	v_mfma_f32_16x16x32_bf16 v[40:43], v[164:167], v[198:201], 0
	v_mfma_f32_16x16x32_bf16 v[32:35], v[148:151], v[206:209], 0
	v_mfma_f32_16x16x32_bf16 v[24:27], v[164:167], v[206:209], 0
	v_mfma_f32_16x16x32_bf16 v[20:23], v[148:151], v[214:217], 0
	v_mfma_f32_16x16x32_bf16 v[12:15], v[164:167], v[214:217], 0
	v_mfma_f32_16x16x32_bf16 v[60:63], v[160:163], v[194:197], v[60:63]
	v_mfma_f32_16x16x32_bf16 v[56:59], v[168:171], v[194:197], v[56:59]
	v_mfma_f32_16x16x32_bf16 v[44:47], v[160:163], v[202:205], v[44:47]
	v_mfma_f32_16x16x32_bf16 v[40:43], v[168:171], v[202:205], v[40:43]
	v_mfma_f32_16x16x32_bf16 v[32:35], v[160:163], v[210:213], v[32:35]
	v_mfma_f32_16x16x32_bf16 v[24:27], v[168:171], v[210:213], v[24:27]
	v_mfma_f32_16x16x32_bf16 v[20:23], v[160:163], v[218:221], v[20:23]
	v_mfma_f32_16x16x32_bf16 v[12:15], v[168:171], v[218:221], v[12:15]
	v_mfma_f32_16x16x32_bf16 v[52:55], v[172:175], v[188:191], 0
	v_mfma_f32_16x16x32_bf16 v[48:51], v[180:183], v[188:191], 0
	v_mfma_f32_16x16x32_bf16 v[36:39], v[172:175], v[198:201], 0
	v_mfma_f32_16x16x32_bf16 v[28:31], v[180:183], v[198:201], 0
	v_mfma_f32_16x16x32_bf16 v[16:19], v[172:175], v[206:209], 0
	v_mfma_f32_16x16x32_bf16 v[8:11], v[180:183], v[206:209], 0
	v_mfma_f32_16x16x32_bf16 v[4:7], v[172:175], v[214:217], 0
	v_mfma_f32_16x16x32_bf16 v[0:3], v[180:183], v[214:217], 0
	v_mfma_f32_16x16x32_bf16 v[52:55], v[176:179], v[194:197], v[52:55]
	v_mfma_f32_16x16x32_bf16 v[48:51], v[184:187], v[194:197], v[48:51]
	v_mfma_f32_16x16x32_bf16 v[36:39], v[176:179], v[202:205], v[36:39]
	v_mfma_f32_16x16x32_bf16 v[28:31], v[184:187], v[202:205], v[28:31]
	v_mfma_f32_16x16x32_bf16 v[16:19], v[176:179], v[210:213], v[16:19]
	v_mfma_f32_16x16x32_bf16 v[8:11], v[184:187], v[210:213], v[8:11]
	v_mfma_f32_16x16x32_bf16 v[4:7], v[176:179], v[218:221], v[4:7]
	v_mfma_f32_16x16x32_bf16 v[0:3], v[184:187], v[218:221], v[0:3]
	s_barrier
	s_add_i32 s51, 0, 0x18000
	v_add_u32_e32 v136, s51, v154
	s_add_i32 s64, 0, 0x1c000
	ds_read_b128 v[148:151], v136
	ds_read_b128 v[160:163], v136 offset:1024
	ds_read_b128 v[164:167], v136 offset:2048
	ds_read_b128 v[168:171], v136 offset:3072
	v_add_u32_e32 v136, s64, v154
	ds_read_b128 v[172:175], v136
	ds_read_b128 v[176:179], v136 offset:1024
	ds_read_b128 v[180:183], v136 offset:2048
	ds_read_b128 v[184:187], v136 offset:3072
	s_add_u32 s46, s46, 0x40000
	s_addc_u32 s47, s47, 0
	s_mov_b32 m0, s22
	v_lshl_add_u64 v[230:231], s[46:47], 0, v[128:129]
	ds_read_b128 v[188:191], v157 offset:32768
	ds_read_b128 v[194:197], v157 offset:33792
	ds_read_b128 v[198:201], v157 offset:34816
	ds_read_b128 v[202:205], v157 offset:35840
	ds_read_b128 v[206:209], v157 offset:36864
	ds_read_b128 v[210:213], v157 offset:37888
	ds_read_b128 v[214:217], v157 offset:38912
	ds_read_b128 v[218:221], v157 offset:39936
	global_load_lds_dwordx4 v[230:231], off
	v_lshl_add_u64 v[230:231], s[46:47], 0, v[132:133]
	s_mov_b32 m0, s23
	s_nop 0
	global_load_lds_dwordx4 v[230:231], off
	s_waitcnt vmcnt(8)
	s_waitcnt lgkmcnt(0)
	s_barrier
	s_waitcnt lgkmcnt(0)
	v_mfma_f32_16x16x32_bf16 v[124:127], v[148:151], v[188:191], v[124:127]
	v_mfma_f32_16x16x32_bf16 v[120:123], v[164:167], v[188:191], v[120:123]
	v_mfma_f32_16x16x32_bf16 v[108:111], v[148:151], v[198:201], v[108:111]
	v_mfma_f32_16x16x32_bf16 v[104:107], v[164:167], v[198:201], v[104:107]
	v_mfma_f32_16x16x32_bf16 v[96:99], v[148:151], v[206:209], v[96:99]
	v_mfma_f32_16x16x32_bf16 v[88:91], v[164:167], v[206:209], v[88:91]
	v_mfma_f32_16x16x32_bf16 v[84:87], v[148:151], v[214:217], v[84:87]
	v_mfma_f32_16x16x32_bf16 v[76:79], v[164:167], v[214:217], v[76:79]
	v_mfma_f32_16x16x32_bf16 v[124:127], v[160:163], v[194:197], v[124:127]
	v_mfma_f32_16x16x32_bf16 v[120:123], v[168:171], v[194:197], v[120:123]
	v_mfma_f32_16x16x32_bf16 v[108:111], v[160:163], v[202:205], v[108:111]
	v_mfma_f32_16x16x32_bf16 v[104:107], v[168:171], v[202:205], v[104:107]
	v_mfma_f32_16x16x32_bf16 v[96:99], v[160:163], v[210:213], v[96:99]
	v_mfma_f32_16x16x32_bf16 v[88:91], v[168:171], v[210:213], v[88:91]
	v_mfma_f32_16x16x32_bf16 v[84:87], v[160:163], v[218:221], v[84:87]
	v_mfma_f32_16x16x32_bf16 v[76:79], v[168:171], v[218:221], v[76:79]
	v_mfma_f32_16x16x32_bf16 v[116:119], v[172:175], v[188:191], v[116:119]
	v_mfma_f32_16x16x32_bf16 v[112:115], v[180:183], v[188:191], v[112:115]
	v_mfma_f32_16x16x32_bf16 v[100:103], v[172:175], v[198:201], v[100:103]
	v_mfma_f32_16x16x32_bf16 v[92:95], v[180:183], v[198:201], v[92:95]
	v_mfma_f32_16x16x32_bf16 v[80:83], v[172:175], v[206:209], v[80:83]
	v_mfma_f32_16x16x32_bf16 v[72:75], v[180:183], v[206:209], v[72:75]
	v_mfma_f32_16x16x32_bf16 v[68:71], v[172:175], v[214:217], v[68:71]
	v_mfma_f32_16x16x32_bf16 v[64:67], v[180:183], v[214:217], v[64:67]
	v_mfma_f32_16x16x32_bf16 v[116:119], v[176:179], v[194:197], v[116:119]
	v_mfma_f32_16x16x32_bf16 v[112:115], v[184:187], v[194:197], v[112:115]
	v_mfma_f32_16x16x32_bf16 v[100:103], v[176:179], v[202:205], v[100:103]
	v_mfma_f32_16x16x32_bf16 v[92:95], v[184:187], v[202:205], v[92:95]
	v_mfma_f32_16x16x32_bf16 v[80:83], v[176:179], v[210:213], v[80:83]
	v_mfma_f32_16x16x32_bf16 v[72:75], v[184:187], v[210:213], v[72:75]
	v_mfma_f32_16x16x32_bf16 v[68:71], v[176:179], v[218:221], v[68:71]
	v_mfma_f32_16x16x32_bf16 v[64:67], v[184:187], v[218:221], v[64:67]
	s_barrier
	s_add_i32 s46, s51, s15
	v_lshl_add_u64 v[222:223], v[222:223], 0, s[18:19]
	s_mov_b32 m0, s46
	ds_read_b128 v[188:191], v157 offset:49152
	ds_read_b128 v[194:197], v157 offset:50176
	ds_read_b128 v[198:201], v157 offset:51200
	ds_read_b128 v[202:205], v157 offset:52224
	ds_read_b128 v[206:209], v157 offset:53248
	ds_read_b128 v[210:213], v157 offset:54272
	ds_read_b128 v[214:217], v157 offset:55296
	ds_read_b128 v[218:221], v157 offset:56320
	global_load_lds_dwordx4 v[222:223], off
	s_add_i32 m0, s46, 0x2000
	s_add_u32 s44, s44, 0x40080
	v_lshl_add_u64 v[222:223], v[224:225], 0, s[18:19]
	s_addc_u32 s45, s45, 0
	s_add_i32 s46, s64, s15
	global_load_lds_dwordx4 v[222:223], off
	v_lshl_add_u64 v[222:223], s[44:45], 0, v[130:131]
	s_mov_b32 m0, s46
	s_nop 0
	global_load_lds_dwordx4 v[222:223], off
	v_lshl_add_u64 v[222:223], s[44:45], 0, v[134:135]
	s_add_i32 m0, s46, 0x2000
	s_nop 0
	global_load_lds_dwordx4 v[222:223], off
	v_lshl_add_u64 v[222:223], v[226:227], 0, s[18:19]
	s_mov_b32 m0, s70
	s_nop 0
	global_load_lds_dwordx4 v[222:223], off
	v_lshl_add_u64 v[222:223], v[228:229], 0, s[18:19]
	s_mov_b32 m0, s71
	s_nop 0
	global_load_lds_dwordx4 v[222:223], off
	s_waitcnt vmcnt(8)
	s_waitcnt lgkmcnt(0)
	s_barrier
	s_waitcnt lgkmcnt(0)
	v_mfma_f32_16x16x32_bf16 v[60:63], v[148:151], v[188:191], v[60:63]
	v_mfma_f32_16x16x32_bf16 v[56:59], v[164:167], v[188:191], v[56:59]
	v_mfma_f32_16x16x32_bf16 v[44:47], v[148:151], v[198:201], v[44:47]
	v_mfma_f32_16x16x32_bf16 v[40:43], v[164:167], v[198:201], v[40:43]
	v_mfma_f32_16x16x32_bf16 v[32:35], v[148:151], v[206:209], v[32:35]
	v_mfma_f32_16x16x32_bf16 v[24:27], v[164:167], v[206:209], v[24:27]
	v_mfma_f32_16x16x32_bf16 v[20:23], v[148:151], v[214:217], v[20:23]
	v_mfma_f32_16x16x32_bf16 v[12:15], v[164:167], v[214:217], v[12:15]
	v_mfma_f32_16x16x32_bf16 v[60:63], v[160:163], v[194:197], v[60:63]
	v_mfma_f32_16x16x32_bf16 v[56:59], v[168:171], v[194:197], v[56:59]
	v_mfma_f32_16x16x32_bf16 v[44:47], v[160:163], v[202:205], v[44:47]
	v_mfma_f32_16x16x32_bf16 v[40:43], v[168:171], v[202:205], v[40:43]
	v_mfma_f32_16x16x32_bf16 v[32:35], v[160:163], v[210:213], v[32:35]
	v_mfma_f32_16x16x32_bf16 v[24:27], v[168:171], v[210:213], v[24:27]
	v_mfma_f32_16x16x32_bf16 v[20:23], v[160:163], v[218:221], v[20:23]
	v_mfma_f32_16x16x32_bf16 v[12:15], v[168:171], v[218:221], v[12:15]
	v_mfma_f32_16x16x32_bf16 v[52:55], v[172:175], v[188:191], v[52:55]
	v_mfma_f32_16x16x32_bf16 v[48:51], v[180:183], v[188:191], v[48:51]
	v_mfma_f32_16x16x32_bf16 v[36:39], v[172:175], v[198:201], v[36:39]
	v_mfma_f32_16x16x32_bf16 v[28:31], v[180:183], v[198:201], v[28:31]
	v_mfma_f32_16x16x32_bf16 v[16:19], v[172:175], v[206:209], v[16:19]
	v_mfma_f32_16x16x32_bf16 v[8:11], v[180:183], v[206:209], v[8:11]
	v_mfma_f32_16x16x32_bf16 v[4:7], v[172:175], v[214:217], v[4:7]
	v_mfma_f32_16x16x32_bf16 v[0:3], v[180:183], v[214:217], v[0:3]
	v_mfma_f32_16x16x32_bf16 v[52:55], v[176:179], v[194:197], v[52:55]
	v_mfma_f32_16x16x32_bf16 v[48:51], v[184:187], v[194:197], v[48:51]
	v_mfma_f32_16x16x32_bf16 v[36:39], v[176:179], v[202:205], v[36:39]
	v_mfma_f32_16x16x32_bf16 v[28:31], v[184:187], v[202:205], v[28:31]
	v_mfma_f32_16x16x32_bf16 v[16:19], v[176:179], v[210:213], v[16:19]
	v_mfma_f32_16x16x32_bf16 v[8:11], v[184:187], v[210:213], v[8:11]
	v_mfma_f32_16x16x32_bf16 v[4:7], v[176:179], v[218:221], v[4:7]
	v_mfma_f32_16x16x32_bf16 v[0:3], v[184:187], v[218:221], v[0:3]
	s_barrier
	s_add_i32 s50, s50, 2
	s_add_u32 s8, s8, 0x100
	s_addc_u32 s9, s9, 0
	s_add_u32 s48, s48, 0x100
	s_addc_u32 s49, s49, 0
	s_cmp_gt_u32 s50, 13
	s_cbranch_scc1 .Lpeel_x0

.Lpeel_x0:
	s_and_b64 vcc, exec, s[34:35]
	s_cbranch_vccz .LBB0_166
	s_barrier

.LBB0_639:
	s_ashr_i32 s13, s12, 31
	s_lshl_b64 s[16:17], s[12:13], 19
	s_add_u32 s16, s74, s16
	s_addc_u32 s17, s75, s17
	s_and_b64 s[18:19], s[38:39], exec
	s_cselect_b32 s13, s17, s37
	s_cselect_b32 s67, s16, s36
	s_ashr_i32 s11, s10, 31
	s_lshl_b64 s[18:19], s[10:11], 19
	s_add_u32 s18, s15, s18
	s_addc_u32 s19, s20, s19
	s_and_b64 s[46:47], s[38:39], exec
	s_cselect_b32 s11, s19, s43
	s_cselect_b32 s68, s18, s42
	s_add_u32 s36, s36, 0x40080
	s_addc_u32 s37, s37, 0
	s_add_u32 s69, s42, 0x100
	s_addc_u32 s70, s43, 0
	s_mov_b32 s71, -2
	ds_read_b128 v[170:173], v164
	ds_read_b128 v[174:177], v164 offset:1024
	ds_read_b128 v[178:181], v164 offset:2048
	ds_read_b128 v[182:185], v164 offset:3072
	ds_read_b128 v[186:189], v165
	ds_read_b128 v[194:197], v165 offset:1024
	ds_read_b128 v[198:201], v165 offset:2048
	ds_read_b128 v[202:205], v165 offset:3072
	s_add_u32 s42, s36, 0xfffc0080
	s_addc_u32 s43, s37, -1
	s_cmp_eq_u32 s71, 12
	s_cselect_b32 s47, s13, s43
	s_cselect_b32 s46, s67, s42
	s_cselect_b32 s43, s11, s70
	s_cselect_b32 s42, s68, s69
	v_lshl_add_u64 v[148:149], s[36:37], 0, v[138:139]
	s_add_i32 m0, s22, 0xc000
	ds_read_b128 v[206:209], v166
	ds_read_b128 v[210:213], v166 offset:1024
	ds_read_b128 v[214:217], v166 offset:2048
	ds_read_b128 v[218:221], v166 offset:3072
	ds_read_b128 v[222:225], v166 offset:4096
	ds_read_b128 v[226:229], v166 offset:5120
	ds_read_b128 v[230:233], v166 offset:6144
	ds_read_b128 v[234:237], v166 offset:7168
	global_load_lds_dwordx4 v[148:149], off
	v_lshl_add_u64 v[148:149], s[36:37], 0, v[140:141]
	s_add_i32 m0, s22, 0xe000
	s_nop 0
	global_load_lds_dwordx4 v[148:149], off
	s_waitcnt vmcnt(8)
	s_waitcnt lgkmcnt(0)
	s_barrier
	s_waitcnt lgkmcnt(0)
	v_mfma_f32_16x16x32_bf16 v[124:127], v[170:173], v[206:209], 0
	v_mfma_f32_16x16x32_bf16 v[120:123], v[178:181], v[206:209], 0
	v_mfma_f32_16x16x32_bf16 v[116:119], v[170:173], v[214:217], 0
	v_mfma_f32_16x16x32_bf16 v[112:115], v[178:181], v[214:217], 0
	v_mfma_f32_16x16x32_bf16 v[100:103], v[170:173], v[222:225], 0
	v_mfma_f32_16x16x32_bf16 v[96:99], v[178:181], v[222:225], 0
	v_mfma_f32_16x16x32_bf16 v[84:87], v[170:173], v[230:233], 0
	v_mfma_f32_16x16x32_bf16 v[80:83], v[178:181], v[230:233], 0
	v_mfma_f32_16x16x32_bf16 v[124:127], v[174:177], v[210:213], v[124:127]
	v_mfma_f32_16x16x32_bf16 v[120:123], v[182:185], v[210:213], v[120:123]
	v_mfma_f32_16x16x32_bf16 v[116:119], v[174:177], v[218:221], v[116:119]
	v_mfma_f32_16x16x32_bf16 v[112:115], v[182:185], v[218:221], v[112:115]
	v_mfma_f32_16x16x32_bf16 v[100:103], v[174:177], v[226:229], v[100:103]
	v_mfma_f32_16x16x32_bf16 v[96:99], v[182:185], v[226:229], v[96:99]
	v_mfma_f32_16x16x32_bf16 v[84:87], v[174:177], v[234:237], v[84:87]
	v_mfma_f32_16x16x32_bf16 v[80:83], v[182:185], v[234:237], v[80:83]
	v_mfma_f32_16x16x32_bf16 v[108:111], v[186:189], v[206:209], 0
	v_mfma_f32_16x16x32_bf16 v[104:107], v[198:201], v[206:209], 0
	v_mfma_f32_16x16x32_bf16 v[92:95], v[186:189], v[214:217], 0
	v_mfma_f32_16x16x32_bf16 v[88:91], v[198:201], v[214:217], 0
	v_mfma_f32_16x16x32_bf16 v[76:79], v[186:189], v[222:225], 0
	v_mfma_f32_16x16x32_bf16 v[72:75], v[198:201], v[222:225], 0
	v_mfma_f32_16x16x32_bf16 v[68:71], v[186:189], v[230:233], 0
	v_mfma_f32_16x16x32_bf16 v[64:67], v[198:201], v[230:233], 0
	v_mfma_f32_16x16x32_bf16 v[108:111], v[194:197], v[210:213], v[108:111]
	v_mfma_f32_16x16x32_bf16 v[104:107], v[202:205], v[210:213], v[104:107]
	v_mfma_f32_16x16x32_bf16 v[92:95], v[194:197], v[218:221], v[92:95]
	v_mfma_f32_16x16x32_bf16 v[88:91], v[202:205], v[218:221], v[88:91]
	v_mfma_f32_16x16x32_bf16 v[76:79], v[194:197], v[226:229], v[76:79]
	v_mfma_f32_16x16x32_bf16 v[72:75], v[202:205], v[226:229], v[72:75]
	v_mfma_f32_16x16x32_bf16 v[68:71], v[194:197], v[234:237], v[68:71]
	v_mfma_f32_16x16x32_bf16 v[64:67], v[202:205], v[234:237], v[64:67]
	s_barrier
	s_add_i32 s72, s65, s14
	v_lshl_add_u64 v[148:149], s[42:43], 0, v[132:133]
	s_mov_b32 m0, s72
	ds_read_b128 v[206:209], v166 offset:16384
	ds_read_b128 v[210:213], v166 offset:17408
	ds_read_b128 v[214:217], v166 offset:18432
	ds_read_b128 v[218:221], v166 offset:19456
	ds_read_b128 v[222:225], v166 offset:20480
	ds_read_b128 v[226:229], v166 offset:21504
	ds_read_b128 v[230:233], v166 offset:22528
	ds_read_b128 v[234:237], v166 offset:23552
	global_load_lds_dwordx4 v[148:149], off
	s_add_i32 m0, s72, 0x2000
	s_add_u32 s72, s42, 0x40000
	v_lshl_add_u64 v[190:191], s[42:43], 0, v[128:129]
	s_addc_u32 s73, s43, 0
	s_add_i32 s78, s66, s14
	global_load_lds_dwordx4 v[190:191], off
	v_lshl_add_u64 v[238:239], s[72:73], 0, v[132:133]
	s_mov_b32 m0, s78
	v_lshl_add_u64 v[240:241], s[46:47], 0, v[130:131]
	global_load_lds_dwordx4 v[238:239], off
	v_lshl_add_u64 v[238:239], s[72:73], 0, v[128:129]
	s_add_i32 m0, s78, 0x2000
	s_nop 0
	global_load_lds_dwordx4 v[238:239], off
	v_lshl_add_u64 v[238:239], s[46:47], 0, v[134:135]
	s_mov_b32 m0, s22
	s_nop 0
	global_load_lds_dwordx4 v[238:239], off
	s_mov_b32 m0, s23
	s_nop 0
	global_load_lds_dwordx4 v[240:241], off
	s_waitcnt vmcnt(8)
	s_waitcnt lgkmcnt(0)
	s_barrier
	s_waitcnt lgkmcnt(0)
	v_mfma_f32_16x16x32_bf16 v[60:63], v[170:173], v[206:209], 0
	v_mfma_f32_16x16x32_bf16 v[56:59], v[178:181], v[206:209], 0
	v_mfma_f32_16x16x32_bf16 v[52:55], v[170:173], v[214:217], 0
	v_mfma_f32_16x16x32_bf16 v[48:51], v[178:181], v[214:217], 0
	v_mfma_f32_16x16x32_bf16 v[36:39], v[170:173], v[222:225], 0
	v_mfma_f32_16x16x32_bf16 v[32:35], v[178:181], v[222:225], 0
	v_mfma_f32_16x16x32_bf16 v[20:23], v[170:173], v[230:233], 0
	v_mfma_f32_16x16x32_bf16 v[16:19], v[178:181], v[230:233], 0
	v_mfma_f32_16x16x32_bf16 v[60:63], v[174:177], v[210:213], v[60:63]
	v_mfma_f32_16x16x32_bf16 v[56:59], v[182:185], v[210:213], v[56:59]
	v_mfma_f32_16x16x32_bf16 v[52:55], v[174:177], v[218:221], v[52:55]
	v_mfma_f32_16x16x32_bf16 v[48:51], v[182:185], v[218:221], v[48:51]
	v_mfma_f32_16x16x32_bf16 v[36:39], v[174:177], v[226:229], v[36:39]
	v_mfma_f32_16x16x32_bf16 v[32:35], v[182:185], v[226:229], v[32:35]
	v_mfma_f32_16x16x32_bf16 v[20:23], v[174:177], v[234:237], v[20:23]
	v_mfma_f32_16x16x32_bf16 v[16:19], v[182:185], v[234:237], v[16:19]
	v_mfma_f32_16x16x32_bf16 v[44:47], v[186:189], v[206:209], 0
	v_mfma_f32_16x16x32_bf16 v[40:43], v[198:201], v[206:209], 0
	v_mfma_f32_16x16x32_bf16 v[28:31], v[186:189], v[214:217], 0
	v_mfma_f32_16x16x32_bf16 v[24:27], v[198:201], v[214:217], 0
	v_mfma_f32_16x16x32_bf16 v[12:15], v[186:189], v[222:225], 0
	v_mfma_f32_16x16x32_bf16 v[8:11], v[198:201], v[222:225], 0
	v_mfma_f32_16x16x32_bf16 v[4:7], v[186:189], v[230:233], 0
	v_mfma_f32_16x16x32_bf16 v[0:3], v[198:201], v[230:233], 0
	v_mfma_f32_16x16x32_bf16 v[44:47], v[194:197], v[210:213], v[44:47]
	v_mfma_f32_16x16x32_bf16 v[40:43], v[202:205], v[210:213], v[40:43]
	v_mfma_f32_16x16x32_bf16 v[28:31], v[194:197], v[218:221], v[28:31]
	v_mfma_f32_16x16x32_bf16 v[24:27], v[202:205], v[218:221], v[24:27]
	v_mfma_f32_16x16x32_bf16 v[12:15], v[194:197], v[226:229], v[12:15]
	v_mfma_f32_16x16x32_bf16 v[8:11], v[202:205], v[226:229], v[8:11]
	v_mfma_f32_16x16x32_bf16 v[4:7], v[194:197], v[234:237], v[4:7]
	v_mfma_f32_16x16x32_bf16 v[0:3], v[202:205], v[234:237], v[0:3]
	s_barrier
	s_add_i32 s72, 0, 0x18000
	v_add_u32_e32 v136, s72, v152
	s_add_i32 s73, 0, 0x1c000
	ds_read_b128 v[170:173], v136
	ds_read_b128 v[174:177], v136 offset:1024
	ds_read_b128 v[178:181], v136 offset:2048
	ds_read_b128 v[182:185], v136 offset:3072
	v_add_u32_e32 v136, s73, v152
	ds_read_b128 v[186:189], v136
	ds_read_b128 v[194:197], v136 offset:1024
	ds_read_b128 v[198:201], v136 offset:2048
	ds_read_b128 v[202:205], v136 offset:3072
	s_add_u32 s46, s46, 0x40000
	s_addc_u32 s47, s47, 0
	s_mov_b32 m0, s33
	v_lshl_add_u64 v[242:243], s[46:47], 0, v[134:135]
	ds_read_b128 v[206:209], v166 offset:32768
	ds_read_b128 v[210:213], v166 offset:33792
	ds_read_b128 v[214:217], v166 offset:34816
	ds_read_b128 v[218:221], v166 offset:35840
	ds_read_b128 v[222:225], v166 offset:36864
	ds_read_b128 v[226:229], v166 offset:37888
	ds_read_b128 v[230:233], v166 offset:38912
	ds_read_b128 v[234:237], v166 offset:39936
	global_load_lds_dwordx4 v[242:243], off
	v_lshl_add_u64 v[242:243], s[46:47], 0, v[130:131]
	s_mov_b32 m0, s48
	s_nop 0
	global_load_lds_dwordx4 v[242:243], off
	s_waitcnt vmcnt(8)
	s_waitcnt lgkmcnt(0)
	s_barrier
	s_waitcnt lgkmcnt(0)
	v_mfma_f32_16x16x32_bf16 v[124:127], v[170:173], v[206:209], v[124:127]
	v_mfma_f32_16x16x32_bf16 v[120:123], v[178:181], v[206:209], v[120:123]
	v_mfma_f32_16x16x32_bf16 v[116:119], v[170:173], v[214:217], v[116:119]
	v_mfma_f32_16x16x32_bf16 v[112:115], v[178:181], v[214:217], v[112:115]
	v_mfma_f32_16x16x32_bf16 v[100:103], v[170:173], v[222:225], v[100:103]
	v_mfma_f32_16x16x32_bf16 v[96:99], v[178:181], v[222:225], v[96:99]
	v_mfma_f32_16x16x32_bf16 v[84:87], v[170:173], v[230:233], v[84:87]
	v_mfma_f32_16x16x32_bf16 v[80:83], v[178:181], v[230:233], v[80:83]
	v_mfma_f32_16x16x32_bf16 v[124:127], v[174:177], v[210:213], v[124:127]
	v_mfma_f32_16x16x32_bf16 v[120:123], v[182:185], v[210:213], v[120:123]
	v_mfma_f32_16x16x32_bf16 v[116:119], v[174:177], v[218:221], v[116:119]
	v_mfma_f32_16x16x32_bf16 v[112:115], v[182:185], v[218:221], v[112:115]
	v_mfma_f32_16x16x32_bf16 v[100:103], v[174:177], v[226:229], v[100:103]
	v_mfma_f32_16x16x32_bf16 v[96:99], v[182:185], v[226:229], v[96:99]
	v_mfma_f32_16x16x32_bf16 v[84:87], v[174:177], v[234:237], v[84:87]
	v_mfma_f32_16x16x32_bf16 v[80:83], v[182:185], v[234:237], v[80:83]
	v_mfma_f32_16x16x32_bf16 v[108:111], v[186:189], v[206:209], v[108:111]
	v_mfma_f32_16x16x32_bf16 v[104:107], v[198:201], v[206:209], v[104:107]
	v_mfma_f32_16x16x32_bf16 v[92:95], v[186:189], v[214:217], v[92:95]
	v_mfma_f32_16x16x32_bf16 v[88:91], v[198:201], v[214:217], v[88:91]
	v_mfma_f32_16x16x32_bf16 v[76:79], v[186:189], v[222:225], v[76:79]
	v_mfma_f32_16x16x32_bf16 v[72:75], v[198:201], v[222:225], v[72:75]
	v_mfma_f32_16x16x32_bf16 v[68:71], v[186:189], v[230:233], v[68:71]
	v_mfma_f32_16x16x32_bf16 v[64:67], v[198:201], v[230:233], v[64:67]
	v_mfma_f32_16x16x32_bf16 v[108:111], v[194:197], v[210:213], v[108:111]
	v_mfma_f32_16x16x32_bf16 v[104:107], v[202:205], v[210:213], v[104:107]
	v_mfma_f32_16x16x32_bf16 v[92:95], v[194:197], v[218:221], v[92:95]
	v_mfma_f32_16x16x32_bf16 v[88:91], v[202:205], v[218:221], v[88:91]
	v_mfma_f32_16x16x32_bf16 v[76:79], v[194:197], v[226:229], v[76:79]
	v_mfma_f32_16x16x32_bf16 v[72:75], v[202:205], v[226:229], v[72:75]
	v_mfma_f32_16x16x32_bf16 v[68:71], v[194:197], v[234:237], v[68:71]
	v_mfma_f32_16x16x32_bf16 v[64:67], v[202:205], v[234:237], v[64:67]
	s_barrier
	s_add_i32 s46, s72, s14
	v_lshl_add_u64 v[148:149], v[148:149], 0, s[4:5]
	s_mov_b32 m0, s46
	ds_read_b128 v[206:209], v166 offset:49152
	ds_read_b128 v[210:213], v166 offset:50176
	ds_read_b128 v[214:217], v166 offset:51200
	ds_read_b128 v[218:221], v166 offset:52224
	ds_read_b128 v[222:225], v166 offset:53248
	ds_read_b128 v[226:229], v166 offset:54272
	ds_read_b128 v[230:233], v166 offset:55296
	ds_read_b128 v[234:237], v166 offset:56320
	global_load_lds_dwordx4 v[148:149], off
	s_add_i32 m0, s46, 0x2000
	s_add_u32 s42, s42, 0x40080
	v_lshl_add_u64 v[148:149], v[190:191], 0, s[4:5]
	s_addc_u32 s43, s43, 0
	s_add_i32 s46, s73, s14
	global_load_lds_dwordx4 v[148:149], off
	v_lshl_add_u64 v[148:149], s[42:43], 0, v[132:133]
	s_mov_b32 m0, s46
	s_nop 0
	global_load_lds_dwordx4 v[148:149], off
	v_lshl_add_u64 v[148:149], s[42:43], 0, v[128:129]
	s_add_i32 m0, s46, 0x2000
	s_nop 0
	global_load_lds_dwordx4 v[148:149], off
	v_lshl_add_u64 v[148:149], v[238:239], 0, s[4:5]
	s_mov_b32 m0, s50
	s_nop 0
	global_load_lds_dwordx4 v[148:149], off
	v_lshl_add_u64 v[148:149], v[240:241], 0, s[4:5]
	s_mov_b32 m0, s51
	s_nop 0
	global_load_lds_dwordx4 v[148:149], off
	s_waitcnt vmcnt(8)
	s_waitcnt lgkmcnt(0)
	s_barrier
	s_waitcnt lgkmcnt(0)
	v_mfma_f32_16x16x32_bf16 v[60:63], v[170:173], v[206:209], v[60:63]
	v_mfma_f32_16x16x32_bf16 v[56:59], v[178:181], v[206:209], v[56:59]
	v_mfma_f32_16x16x32_bf16 v[52:55], v[170:173], v[214:217], v[52:55]
	v_mfma_f32_16x16x32_bf16 v[48:51], v[178:181], v[214:217], v[48:51]
	v_mfma_f32_16x16x32_bf16 v[36:39], v[170:173], v[222:225], v[36:39]
	v_mfma_f32_16x16x32_bf16 v[32:35], v[178:181], v[222:225], v[32:35]
	v_mfma_f32_16x16x32_bf16 v[20:23], v[170:173], v[230:233], v[20:23]
	v_mfma_f32_16x16x32_bf16 v[16:19], v[178:181], v[230:233], v[16:19]
	v_mfma_f32_16x16x32_bf16 v[60:63], v[174:177], v[210:213], v[60:63]
	v_mfma_f32_16x16x32_bf16 v[56:59], v[182:185], v[210:213], v[56:59]
	v_mfma_f32_16x16x32_bf16 v[52:55], v[174:177], v[218:221], v[52:55]
	v_mfma_f32_16x16x32_bf16 v[48:51], v[182:185], v[218:221], v[48:51]
	v_mfma_f32_16x16x32_bf16 v[36:39], v[174:177], v[226:229], v[36:39]
	v_mfma_f32_16x16x32_bf16 v[32:35], v[182:185], v[226:229], v[32:35]
	v_mfma_f32_16x16x32_bf16 v[20:23], v[174:177], v[234:237], v[20:23]
	v_mfma_f32_16x16x32_bf16 v[16:19], v[182:185], v[234:237], v[16:19]
	v_mfma_f32_16x16x32_bf16 v[44:47], v[186:189], v[206:209], v[44:47]
	v_mfma_f32_16x16x32_bf16 v[40:43], v[198:201], v[206:209], v[40:43]
	v_mfma_f32_16x16x32_bf16 v[28:31], v[186:189], v[214:217], v[28:31]
	v_mfma_f32_16x16x32_bf16 v[24:27], v[198:201], v[214:217], v[24:27]
	v_mfma_f32_16x16x32_bf16 v[12:15], v[186:189], v[222:225], v[12:15]
	v_mfma_f32_16x16x32_bf16 v[8:11], v[198:201], v[222:225], v[8:11]
	v_mfma_f32_16x16x32_bf16 v[4:7], v[186:189], v[230:233], v[4:7]
	v_mfma_f32_16x16x32_bf16 v[0:3], v[198:201], v[230:233], v[0:3]
	v_mfma_f32_16x16x32_bf16 v[44:47], v[194:197], v[210:213], v[44:47]
	v_mfma_f32_16x16x32_bf16 v[40:43], v[202:205], v[210:213], v[40:43]
	v_mfma_f32_16x16x32_bf16 v[28:31], v[194:197], v[218:221], v[28:31]
	v_mfma_f32_16x16x32_bf16 v[24:27], v[202:205], v[218:221], v[24:27]
	v_mfma_f32_16x16x32_bf16 v[12:15], v[194:197], v[226:229], v[12:15]
	v_mfma_f32_16x16x32_bf16 v[8:11], v[202:205], v[226:229], v[8:11]
	v_mfma_f32_16x16x32_bf16 v[4:7], v[194:197], v[234:237], v[4:7]
	v_mfma_f32_16x16x32_bf16 v[0:3], v[202:205], v[234:237], v[0:3]
	s_barrier
	s_add_i32 s71, s71, 2
	s_add_u32 s36, s36, 0x100
	s_addc_u32 s37, s37, 0
	s_add_u32 s69, s69, 0x100
	s_addc_u32 s70, s70, 0
	s_cmp_gt_u32 s71, 13
	s_cbranch_scc1 .Lpeel_x1

.Lpeel_x1:
	s_and_b64 vcc, exec, s[6:7]
	s_cbranch_vccz .LBB0_643
	s_barrier

.LBB0_676:
	s_ashr_i32 s13, s12, 31
	s_lshl_b64 s[16:17], s[12:13], 19
	s_add_u32 s16, s15, s16
	s_addc_u32 s17, s20, s17
	s_and_b64 s[18:19], s[38:39], exec
	s_cselect_b32 s13, s17, s37
	s_cselect_b32 s53, s16, s36
	s_ashr_i32 s11, s10, 31
	s_lshl_b64 s[18:19], s[10:11], 19
	s_add_u32 s18, s74, s18
	s_addc_u32 s19, s75, s19
	s_and_b64 s[46:47], s[38:39], exec
	s_cselect_b32 s11, s19, s43
	s_cselect_b32 s64, s18, s42
	s_add_u32 s36, s36, 0x40080
	s_addc_u32 s37, s37, 0
	s_add_u32 s65, s42, 0x100
	s_addc_u32 s66, s43, 0
	s_mov_b32 s67, -2
	ds_read_b128 v[150:153], v147
	ds_read_b128 v[154:157], v147 offset:1024
	ds_read_b128 v[158:161], v147 offset:2048
	ds_read_b128 v[162:165], v147 offset:3072
	ds_read_b128 v[166:169], v148
	ds_read_b128 v[170:173], v148 offset:1024
	ds_read_b128 v[174:177], v148 offset:2048
	ds_read_b128 v[178:181], v148 offset:3072
	s_add_u32 s42, s36, 0xfffc0080
	s_addc_u32 s43, s37, -1
	s_cmp_eq_u32 s67, 12
	s_cselect_b32 s47, s13, s43
	s_cselect_b32 s46, s53, s42
	s_cselect_b32 s43, s11, s66
	s_cselect_b32 s42, s64, s65
	v_lshl_add_u64 v[190:191], s[36:37], 0, v[136:137]
	s_add_i32 m0, s21, 0xc000
	ds_read_b128 v[182:185], v149
	ds_read_b128 v[186:189], v149 offset:1024
	ds_read_b128 v[194:197], v149 offset:2048
	ds_read_b128 v[198:201], v149 offset:3072
	ds_read_b128 v[202:205], v149 offset:4096
	ds_read_b128 v[206:209], v149 offset:5120
	ds_read_b128 v[210:213], v149 offset:6144
	ds_read_b128 v[214:217], v149 offset:7168
	global_load_lds_dwordx4 v[190:191], off
	v_lshl_add_u64 v[190:191], s[36:37], 0, v[138:139]
	s_add_i32 m0, s21, 0xe000
	s_nop 0
	global_load_lds_dwordx4 v[190:191], off
	s_waitcnt vmcnt(8)
	s_waitcnt lgkmcnt(0)
	s_barrier
	s_waitcnt lgkmcnt(0)
	v_mfma_f32_16x16x32_bf16 v[124:127], v[150:153], v[182:185], 0
	v_mfma_f32_16x16x32_bf16 v[120:123], v[158:161], v[182:185], 0
	v_mfma_f32_16x16x32_bf16 v[116:119], v[150:153], v[194:197], 0
	v_mfma_f32_16x16x32_bf16 v[112:115], v[158:161], v[194:197], 0
	v_mfma_f32_16x16x32_bf16 v[100:103], v[150:153], v[202:205], 0
	v_mfma_f32_16x16x32_bf16 v[96:99], v[158:161], v[202:205], 0
	v_mfma_f32_16x16x32_bf16 v[84:87], v[150:153], v[210:213], 0
	v_mfma_f32_16x16x32_bf16 v[80:83], v[158:161], v[210:213], 0
	v_mfma_f32_16x16x32_bf16 v[124:127], v[154:157], v[186:189], v[124:127]
	v_mfma_f32_16x16x32_bf16 v[120:123], v[162:165], v[186:189], v[120:123]
	v_mfma_f32_16x16x32_bf16 v[116:119], v[154:157], v[198:201], v[116:119]
	v_mfma_f32_16x16x32_bf16 v[112:115], v[162:165], v[198:201], v[112:115]
	v_mfma_f32_16x16x32_bf16 v[100:103], v[154:157], v[206:209], v[100:103]
	v_mfma_f32_16x16x32_bf16 v[96:99], v[162:165], v[206:209], v[96:99]
	v_mfma_f32_16x16x32_bf16 v[84:87], v[154:157], v[214:217], v[84:87]
	v_mfma_f32_16x16x32_bf16 v[80:83], v[162:165], v[214:217], v[80:83]
	v_mfma_f32_16x16x32_bf16 v[108:111], v[166:169], v[182:185], 0
	v_mfma_f32_16x16x32_bf16 v[104:107], v[174:177], v[182:185], 0
	v_mfma_f32_16x16x32_bf16 v[92:95], v[166:169], v[194:197], 0
	v_mfma_f32_16x16x32_bf16 v[88:91], v[174:177], v[194:197], 0
	v_mfma_f32_16x16x32_bf16 v[76:79], v[166:169], v[202:205], 0
	v_mfma_f32_16x16x32_bf16 v[72:75], v[174:177], v[202:205], 0
	v_mfma_f32_16x16x32_bf16 v[68:71], v[166:169], v[210:213], 0
	v_mfma_f32_16x16x32_bf16 v[64:67], v[174:177], v[210:213], 0
	v_mfma_f32_16x16x32_bf16 v[108:111], v[170:173], v[186:189], v[108:111]
	v_mfma_f32_16x16x32_bf16 v[104:107], v[178:181], v[186:189], v[104:107]
	v_mfma_f32_16x16x32_bf16 v[92:95], v[170:173], v[198:201], v[92:95]
	v_mfma_f32_16x16x32_bf16 v[88:91], v[178:181], v[198:201], v[88:91]
	v_mfma_f32_16x16x32_bf16 v[76:79], v[170:173], v[206:209], v[76:79]
	v_mfma_f32_16x16x32_bf16 v[72:75], v[178:181], v[206:209], v[72:75]
	v_mfma_f32_16x16x32_bf16 v[68:71], v[170:173], v[214:217], v[68:71]
	v_mfma_f32_16x16x32_bf16 v[64:67], v[178:181], v[214:217], v[64:67]
	s_barrier
	s_add_i32 s68, s51, s14
	v_lshl_add_u64 v[190:191], s[42:43], 0, v[132:133]
	s_mov_b32 m0, s68
	ds_read_b128 v[182:185], v149 offset:16384
	ds_read_b128 v[186:189], v149 offset:17408
	ds_read_b128 v[194:197], v149 offset:18432
	ds_read_b128 v[198:201], v149 offset:19456
	ds_read_b128 v[202:205], v149 offset:20480
	ds_read_b128 v[206:209], v149 offset:21504
	ds_read_b128 v[210:213], v149 offset:22528
	ds_read_b128 v[214:217], v149 offset:23552
	global_load_lds_dwordx4 v[190:191], off
	s_add_i32 m0, s68, 0x2000
	s_add_u32 s68, s42, 0x40000
	v_lshl_add_u64 v[218:219], s[42:43], 0, v[128:129]
	s_addc_u32 s69, s43, 0
	s_add_i32 s70, s52, s14
	global_load_lds_dwordx4 v[218:219], off
	v_lshl_add_u64 v[220:221], s[68:69], 0, v[132:133]
	s_mov_b32 m0, s70
	v_lshl_add_u64 v[222:223], s[46:47], 0, v[130:131]
	global_load_lds_dwordx4 v[220:221], off
	v_lshl_add_u64 v[220:221], s[68:69], 0, v[128:129]
	s_add_i32 m0, s70, 0x2000
	s_nop 0
	global_load_lds_dwordx4 v[220:221], off
	v_lshl_add_u64 v[220:221], s[46:47], 0, v[134:135]
	s_mov_b32 m0, s21
	s_nop 0
	global_load_lds_dwordx4 v[220:221], off
	s_mov_b32 m0, s22
	s_nop 0
	global_load_lds_dwordx4 v[222:223], off
	s_waitcnt vmcnt(8)
	s_waitcnt lgkmcnt(0)
	s_barrier
	s_waitcnt lgkmcnt(0)
	v_mfma_f32_16x16x32_bf16 v[60:63], v[150:153], v[182:185], 0
	v_mfma_f32_16x16x32_bf16 v[56:59], v[158:161], v[182:185], 0
	v_mfma_f32_16x16x32_bf16 v[52:55], v[150:153], v[194:197], 0
	v_mfma_f32_16x16x32_bf16 v[48:51], v[158:161], v[194:197], 0
	v_mfma_f32_16x16x32_bf16 v[36:39], v[150:153], v[202:205], 0
	v_mfma_f32_16x16x32_bf16 v[32:35], v[158:161], v[202:205], 0
	v_mfma_f32_16x16x32_bf16 v[20:23], v[150:153], v[210:213], 0
	v_mfma_f32_16x16x32_bf16 v[16:19], v[158:161], v[210:213], 0
	v_mfma_f32_16x16x32_bf16 v[60:63], v[154:157], v[186:189], v[60:63]
	v_mfma_f32_16x16x32_bf16 v[56:59], v[162:165], v[186:189], v[56:59]
	v_mfma_f32_16x16x32_bf16 v[52:55], v[154:157], v[198:201], v[52:55]
	v_mfma_f32_16x16x32_bf16 v[48:51], v[162:165], v[198:201], v[48:51]
	v_mfma_f32_16x16x32_bf16 v[36:39], v[154:157], v[206:209], v[36:39]
	v_mfma_f32_16x16x32_bf16 v[32:35], v[162:165], v[206:209], v[32:35]
	v_mfma_f32_16x16x32_bf16 v[20:23], v[154:157], v[214:217], v[20:23]
	v_mfma_f32_16x16x32_bf16 v[16:19], v[162:165], v[214:217], v[16:19]
	v_mfma_f32_16x16x32_bf16 v[44:47], v[166:169], v[182:185], 0
	v_mfma_f32_16x16x32_bf16 v[40:43], v[174:177], v[182:185], 0
	v_mfma_f32_16x16x32_bf16 v[28:31], v[166:169], v[194:197], 0
	v_mfma_f32_16x16x32_bf16 v[24:27], v[174:177], v[194:197], 0
	v_mfma_f32_16x16x32_bf16 v[12:15], v[166:169], v[202:205], 0
	v_mfma_f32_16x16x32_bf16 v[8:11], v[174:177], v[202:205], 0
	v_mfma_f32_16x16x32_bf16 v[4:7], v[166:169], v[210:213], 0
	v_mfma_f32_16x16x32_bf16 v[0:3], v[174:177], v[210:213], 0
	v_mfma_f32_16x16x32_bf16 v[44:47], v[170:173], v[186:189], v[44:47]
	v_mfma_f32_16x16x32_bf16 v[40:43], v[178:181], v[186:189], v[40:43]
	v_mfma_f32_16x16x32_bf16 v[28:31], v[170:173], v[198:201], v[28:31]
	v_mfma_f32_16x16x32_bf16 v[24:27], v[178:181], v[198:201], v[24:27]
	v_mfma_f32_16x16x32_bf16 v[12:15], v[170:173], v[206:209], v[12:15]
	v_mfma_f32_16x16x32_bf16 v[8:11], v[178:181], v[206:209], v[8:11]
	v_mfma_f32_16x16x32_bf16 v[4:7], v[170:173], v[214:217], v[4:7]
	v_mfma_f32_16x16x32_bf16 v[0:3], v[178:181], v[214:217], v[0:3]
	s_barrier
	s_add_i32 s68, 0, 0x18000
	s_add_i32 s69, 0, 0x1c000
	v_add_u32_e32 v162, s68, v145
	v_add_u32_e32 v178, s69, v145
	ds_read_b128 v[150:153], v162
	ds_read_b128 v[154:157], v162 offset:1024
	ds_read_b128 v[158:161], v162 offset:2048
	ds_read_b128 v[162:165], v162 offset:3072
	ds_read_b128 v[166:169], v178
	ds_read_b128 v[170:173], v178 offset:1024
	ds_read_b128 v[174:177], v178 offset:2048
	ds_read_b128 v[178:181], v178 offset:3072
	s_add_u32 s46, s46, 0x40000
	s_addc_u32 s47, s47, 0
	s_mov_b32 m0, s23
	v_lshl_add_u64 v[224:225], s[46:47], 0, v[134:135]
	ds_read_b128 v[182:185], v149 offset:32768
	ds_read_b128 v[186:189], v149 offset:33792
	ds_read_b128 v[194:197], v149 offset:34816
	ds_read_b128 v[198:201], v149 offset:35840
	ds_read_b128 v[202:205], v149 offset:36864
	ds_read_b128 v[206:209], v149 offset:37888
	ds_read_b128 v[210:213], v149 offset:38912
	ds_read_b128 v[214:217], v149 offset:39936
	global_load_lds_dwordx4 v[224:225], off
	v_lshl_add_u64 v[224:225], s[46:47], 0, v[130:131]
	s_mov_b32 m0, s33
	s_nop 0
	global_load_lds_dwordx4 v[224:225], off
	s_waitcnt vmcnt(8)
	s_waitcnt lgkmcnt(0)
	s_barrier
	s_waitcnt lgkmcnt(0)
	v_mfma_f32_16x16x32_bf16 v[124:127], v[150:153], v[182:185], v[124:127]
	v_mfma_f32_16x16x32_bf16 v[120:123], v[158:161], v[182:185], v[120:123]
	v_mfma_f32_16x16x32_bf16 v[116:119], v[150:153], v[194:197], v[116:119]
	v_mfma_f32_16x16x32_bf16 v[112:115], v[158:161], v[194:197], v[112:115]
	v_mfma_f32_16x16x32_bf16 v[100:103], v[150:153], v[202:205], v[100:103]
	v_mfma_f32_16x16x32_bf16 v[96:99], v[158:161], v[202:205], v[96:99]
	v_mfma_f32_16x16x32_bf16 v[84:87], v[150:153], v[210:213], v[84:87]
	v_mfma_f32_16x16x32_bf16 v[80:83], v[158:161], v[210:213], v[80:83]
	v_mfma_f32_16x16x32_bf16 v[124:127], v[154:157], v[186:189], v[124:127]
	v_mfma_f32_16x16x32_bf16 v[120:123], v[162:165], v[186:189], v[120:123]
	v_mfma_f32_16x16x32_bf16 v[116:119], v[154:157], v[198:201], v[116:119]
	v_mfma_f32_16x16x32_bf16 v[112:115], v[162:165], v[198:201], v[112:115]
	v_mfma_f32_16x16x32_bf16 v[100:103], v[154:157], v[206:209], v[100:103]
	v_mfma_f32_16x16x32_bf16 v[96:99], v[162:165], v[206:209], v[96:99]
	v_mfma_f32_16x16x32_bf16 v[84:87], v[154:157], v[214:217], v[84:87]
	v_mfma_f32_16x16x32_bf16 v[80:83], v[162:165], v[214:217], v[80:83]
	v_mfma_f32_16x16x32_bf16 v[108:111], v[166:169], v[182:185], v[108:111]
	v_mfma_f32_16x16x32_bf16 v[104:107], v[174:177], v[182:185], v[104:107]
	v_mfma_f32_16x16x32_bf16 v[92:95], v[166:169], v[194:197], v[92:95]
	v_mfma_f32_16x16x32_bf16 v[88:91], v[174:177], v[194:197], v[88:91]
	v_mfma_f32_16x16x32_bf16 v[76:79], v[166:169], v[202:205], v[76:79]
	v_mfma_f32_16x16x32_bf16 v[72:75], v[174:177], v[202:205], v[72:75]
	v_mfma_f32_16x16x32_bf16 v[68:71], v[166:169], v[210:213], v[68:71]
	v_mfma_f32_16x16x32_bf16 v[64:67], v[174:177], v[210:213], v[64:67]
	v_mfma_f32_16x16x32_bf16 v[108:111], v[170:173], v[186:189], v[108:111]
	v_mfma_f32_16x16x32_bf16 v[104:107], v[178:181], v[186:189], v[104:107]
	v_mfma_f32_16x16x32_bf16 v[92:95], v[170:173], v[198:201], v[92:95]
	v_mfma_f32_16x16x32_bf16 v[88:91], v[178:181], v[198:201], v[88:91]
	v_mfma_f32_16x16x32_bf16 v[76:79], v[170:173], v[206:209], v[76:79]
	v_mfma_f32_16x16x32_bf16 v[72:75], v[178:181], v[206:209], v[72:75]
	v_mfma_f32_16x16x32_bf16 v[68:71], v[170:173], v[214:217], v[68:71]
	v_mfma_f32_16x16x32_bf16 v[64:67], v[178:181], v[214:217], v[64:67]
	s_barrier
	s_add_i32 s46, s68, s14
	v_lshl_add_u64 v[190:191], v[190:191], 0, s[4:5]
	s_mov_b32 m0, s46
	ds_read_b128 v[182:185], v149 offset:49152
	ds_read_b128 v[186:189], v149 offset:50176
	ds_read_b128 v[194:197], v149 offset:51200
	ds_read_b128 v[198:201], v149 offset:52224
	ds_read_b128 v[202:205], v149 offset:53248
	ds_read_b128 v[206:209], v149 offset:54272
	ds_read_b128 v[210:213], v149 offset:55296
	ds_read_b128 v[214:217], v149 offset:56320
	global_load_lds_dwordx4 v[190:191], off
	s_add_i32 m0, s46, 0x2000
	s_add_u32 s42, s42, 0x40080
	v_lshl_add_u64 v[190:191], v[218:219], 0, s[4:5]
	s_addc_u32 s43, s43, 0
	s_add_i32 s46, s69, s14
	global_load_lds_dwordx4 v[190:191], off
	v_lshl_add_u64 v[190:191], s[42:43], 0, v[132:133]
	s_mov_b32 m0, s46
	s_nop 0
	global_load_lds_dwordx4 v[190:191], off
	v_lshl_add_u64 v[190:191], s[42:43], 0, v[128:129]
	s_add_i32 m0, s46, 0x2000
	s_nop 0
	global_load_lds_dwordx4 v[190:191], off
	v_lshl_add_u64 v[190:191], v[220:221], 0, s[4:5]
	s_mov_b32 m0, s49
	s_nop 0
	global_load_lds_dwordx4 v[190:191], off
	v_lshl_add_u64 v[190:191], v[222:223], 0, s[4:5]
	s_mov_b32 m0, s50
	s_nop 0
	global_load_lds_dwordx4 v[190:191], off
	s_waitcnt vmcnt(8)
	s_waitcnt lgkmcnt(0)
	s_barrier
	s_waitcnt lgkmcnt(0)
	v_mfma_f32_16x16x32_bf16 v[60:63], v[150:153], v[182:185], v[60:63]
	v_mfma_f32_16x16x32_bf16 v[56:59], v[158:161], v[182:185], v[56:59]
	v_mfma_f32_16x16x32_bf16 v[52:55], v[150:153], v[194:197], v[52:55]
	v_mfma_f32_16x16x32_bf16 v[48:51], v[158:161], v[194:197], v[48:51]
	v_mfma_f32_16x16x32_bf16 v[36:39], v[150:153], v[202:205], v[36:39]
	v_mfma_f32_16x16x32_bf16 v[32:35], v[158:161], v[202:205], v[32:35]
	v_mfma_f32_16x16x32_bf16 v[20:23], v[150:153], v[210:213], v[20:23]
	v_mfma_f32_16x16x32_bf16 v[16:19], v[158:161], v[210:213], v[16:19]
	v_mfma_f32_16x16x32_bf16 v[60:63], v[154:157], v[186:189], v[60:63]
	v_mfma_f32_16x16x32_bf16 v[56:59], v[162:165], v[186:189], v[56:59]
	v_mfma_f32_16x16x32_bf16 v[52:55], v[154:157], v[198:201], v[52:55]
	v_mfma_f32_16x16x32_bf16 v[48:51], v[162:165], v[198:201], v[48:51]
	v_mfma_f32_16x16x32_bf16 v[36:39], v[154:157], v[206:209], v[36:39]
	v_mfma_f32_16x16x32_bf16 v[32:35], v[162:165], v[206:209], v[32:35]
	v_mfma_f32_16x16x32_bf16 v[20:23], v[154:157], v[214:217], v[20:23]
	v_mfma_f32_16x16x32_bf16 v[16:19], v[162:165], v[214:217], v[16:19]
	v_mfma_f32_16x16x32_bf16 v[44:47], v[166:169], v[182:185], v[44:47]
	v_mfma_f32_16x16x32_bf16 v[40:43], v[174:177], v[182:185], v[40:43]
	v_mfma_f32_16x16x32_bf16 v[28:31], v[166:169], v[194:197], v[28:31]
	v_mfma_f32_16x16x32_bf16 v[24:27], v[174:177], v[194:197], v[24:27]
	v_mfma_f32_16x16x32_bf16 v[12:15], v[166:169], v[202:205], v[12:15]
	v_mfma_f32_16x16x32_bf16 v[8:11], v[174:177], v[202:205], v[8:11]
	v_mfma_f32_16x16x32_bf16 v[4:7], v[166:169], v[210:213], v[4:7]
	v_mfma_f32_16x16x32_bf16 v[0:3], v[174:177], v[210:213], v[0:3]
	v_mfma_f32_16x16x32_bf16 v[44:47], v[170:173], v[186:189], v[44:47]
	v_mfma_f32_16x16x32_bf16 v[40:43], v[178:181], v[186:189], v[40:43]
	v_mfma_f32_16x16x32_bf16 v[28:31], v[170:173], v[198:201], v[28:31]
	v_mfma_f32_16x16x32_bf16 v[24:27], v[178:181], v[198:201], v[24:27]
	v_mfma_f32_16x16x32_bf16 v[12:15], v[170:173], v[206:209], v[12:15]
	v_mfma_f32_16x16x32_bf16 v[8:11], v[178:181], v[206:209], v[8:11]
	v_mfma_f32_16x16x32_bf16 v[4:7], v[170:173], v[214:217], v[4:7]
	v_mfma_f32_16x16x32_bf16 v[0:3], v[178:181], v[214:217], v[0:3]
	s_barrier
	s_add_i32 s67, s67, 2
	s_add_u32 s36, s36, 0x100
	s_addc_u32 s37, s37, 0
	s_add_u32 s65, s65, 0x100
	s_addc_u32 s66, s66, 0
	s_cmp_gt_u32 s67, 13
	s_cbranch_scc1 .Lpeel_x2

.LBB0_884:
	s_ashr_i32 s17, s16, 31
	s_lshl_b64 s[18:19], s[16:17], 19
	s_add_u32 s18, s28, s18
	s_addc_u32 s19, s29, s19
	s_and_b64 s[24:25], s[42:43], exec
	s_cselect_b32 s17, s19, s31
	s_cselect_b32 s27, s18, s30
	s_ashr_i32 s13, s12, 31
	s_lshl_b64 s[24:25], s[12:13], 19
	s_add_u32 s24, s60, s24
	s_addc_u32 s25, s61, s25
	s_and_b64 s[36:37], s[42:43], exec
	s_cselect_b32 s13, s25, s35
	s_cselect_b32 s50, s24, s34
	s_add_u32 s30, s30, 0x40080
	s_addc_u32 s31, s31, 0
	s_add_u32 s51, s34, 0x100
	s_addc_u32 s52, s35, 0
	s_mov_b32 s53, -2
	s_waitcnt lgkmcnt(0)
	ds_read_b128 v[140:143], v149
	ds_read_b128 v[152:155], v149 offset:1024
	ds_read_b128 v[156:159], v149 offset:2048
	ds_read_b128 v[160:163], v149 offset:3072
	ds_read_b128 v[164:167], v150
	ds_read_b128 v[168:171], v150 offset:1024
	ds_read_b128 v[172:175], v150 offset:2048
	ds_read_b128 v[176:179], v150 offset:3072
	s_add_u32 s34, s30, 0xfffc0080
	s_addc_u32 s35, s31, -1
	s_cmp_eq_u32 s53, 12
	s_cselect_b32 s37, s17, s35
	s_cselect_b32 s36, s27, s34
	s_cselect_b32 s35, s13, s52
	s_cselect_b32 s34, s50, s51
	v_lshl_add_u64 v[214:215], s[30:31], 0, v[132:133]
	s_add_i32 m0, s15, 0xc000
	ds_read_b128 v[180:183], v151
	ds_read_b128 v[184:187], v151 offset:1024
	ds_read_b128 v[188:191], v151 offset:2048
	ds_read_b128 v[194:197], v151 offset:3072
	ds_read_b128 v[198:201], v151 offset:4096
	ds_read_b128 v[202:205], v151 offset:5120
	ds_read_b128 v[206:209], v151 offset:6144
	ds_read_b128 v[210:213], v151 offset:7168
	global_load_lds_dwordx4 v[214:215], off
	v_lshl_add_u64 v[214:215], s[30:31], 0, v[134:135]
	s_add_i32 m0, s15, 0xe000
	s_nop 0
	global_load_lds_dwordx4 v[214:215], off
	s_waitcnt vmcnt(8)
	s_waitcnt lgkmcnt(0)
	s_barrier
	s_waitcnt lgkmcnt(0)
	v_mfma_f32_16x16x32_bf16 v[124:127], v[140:143], v[180:183], 0
	v_mfma_f32_16x16x32_bf16 v[120:123], v[156:159], v[180:183], 0
	v_mfma_f32_16x16x32_bf16 v[108:111], v[140:143], v[188:191], 0
	v_mfma_f32_16x16x32_bf16 v[104:107], v[156:159], v[188:191], 0
	v_mfma_f32_16x16x32_bf16 v[92:95], v[140:143], v[198:201], 0
	v_mfma_f32_16x16x32_bf16 v[88:91], v[156:159], v[198:201], 0
	v_mfma_f32_16x16x32_bf16 v[76:79], v[140:143], v[206:209], 0
	v_mfma_f32_16x16x32_bf16 v[72:75], v[156:159], v[206:209], 0
	v_mfma_f32_16x16x32_bf16 v[124:127], v[152:155], v[184:187], v[124:127]
	v_mfma_f32_16x16x32_bf16 v[120:123], v[160:163], v[184:187], v[120:123]
	v_mfma_f32_16x16x32_bf16 v[108:111], v[152:155], v[194:197], v[108:111]
	v_mfma_f32_16x16x32_bf16 v[104:107], v[160:163], v[194:197], v[104:107]
	v_mfma_f32_16x16x32_bf16 v[92:95], v[152:155], v[202:205], v[92:95]
	v_mfma_f32_16x16x32_bf16 v[88:91], v[160:163], v[202:205], v[88:91]
	v_mfma_f32_16x16x32_bf16 v[76:79], v[152:155], v[210:213], v[76:79]
	v_mfma_f32_16x16x32_bf16 v[72:75], v[160:163], v[210:213], v[72:75]
	v_mfma_f32_16x16x32_bf16 v[116:119], v[164:167], v[180:183], 0
	v_mfma_f32_16x16x32_bf16 v[112:115], v[172:175], v[180:183], 0
	v_mfma_f32_16x16x32_bf16 v[100:103], v[164:167], v[188:191], 0
	v_mfma_f32_16x16x32_bf16 v[96:99], v[172:175], v[188:191], 0
	v_mfma_f32_16x16x32_bf16 v[84:87], v[164:167], v[198:201], 0
	v_mfma_f32_16x16x32_bf16 v[80:83], v[172:175], v[198:201], 0
	v_mfma_f32_16x16x32_bf16 v[68:71], v[164:167], v[206:209], 0
	v_mfma_f32_16x16x32_bf16 v[64:67], v[172:175], v[206:209], 0
	v_mfma_f32_16x16x32_bf16 v[116:119], v[168:171], v[184:187], v[116:119]
	v_mfma_f32_16x16x32_bf16 v[112:115], v[176:179], v[184:187], v[112:115]
	v_mfma_f32_16x16x32_bf16 v[100:103], v[168:171], v[194:197], v[100:103]
	v_mfma_f32_16x16x32_bf16 v[96:99], v[176:179], v[194:197], v[96:99]
	v_mfma_f32_16x16x32_bf16 v[84:87], v[168:171], v[202:205], v[84:87]
	v_mfma_f32_16x16x32_bf16 v[80:83], v[176:179], v[202:205], v[80:83]
	v_mfma_f32_16x16x32_bf16 v[68:71], v[168:171], v[210:213], v[68:71]
	v_mfma_f32_16x16x32_bf16 v[64:67], v[176:179], v[210:213], v[64:67]
	s_barrier
	s_add_i32 s54, s47, s14
	v_lshl_add_u64 v[214:215], s[34:35], 0, v[128:129]
	s_mov_b32 m0, s54
	ds_read_b128 v[180:183], v151 offset:16384
	ds_read_b128 v[184:187], v151 offset:17408
	ds_read_b128 v[188:191], v151 offset:18432
	ds_read_b128 v[194:197], v151 offset:19456
	ds_read_b128 v[198:201], v151 offset:20480
	ds_read_b128 v[202:205], v151 offset:21504
	ds_read_b128 v[206:209], v151 offset:22528
	ds_read_b128 v[210:213], v151 offset:23552
	global_load_lds_dwordx4 v[214:215], off
	s_add_i32 m0, s54, 0x2000
	s_add_u32 s54, s34, 0x40000
	v_lshl_add_u64 v[216:217], s[34:35], 0, v[130:131]
	s_addc_u32 s55, s35, 0
	s_add_i32 s56, s48, s14
	global_load_lds_dwordx4 v[216:217], off
	v_lshl_add_u64 v[218:219], s[54:55], 0, v[128:129]
	s_mov_b32 m0, s56
	v_lshl_add_u64 v[220:221], s[36:37], 0, v[130:131]
	global_load_lds_dwordx4 v[218:219], off
	v_lshl_add_u64 v[218:219], s[54:55], 0, v[130:131]
	s_add_i32 m0, s56, 0x2000
	s_nop 0
	global_load_lds_dwordx4 v[218:219], off
	v_lshl_add_u64 v[218:219], s[36:37], 0, v[128:129]
	s_mov_b32 m0, s15
	s_nop 0
	global_load_lds_dwordx4 v[218:219], off
	s_mov_b32 m0, s20
	s_nop 0
	global_load_lds_dwordx4 v[220:221], off
	s_waitcnt vmcnt(8)
	s_waitcnt lgkmcnt(0)
	s_barrier
	s_waitcnt lgkmcnt(0)
	v_mfma_f32_16x16x32_bf16 v[60:63], v[140:143], v[180:183], 0
	v_mfma_f32_16x16x32_bf16 v[56:59], v[156:159], v[180:183], 0
	v_mfma_f32_16x16x32_bf16 v[44:47], v[140:143], v[188:191], 0
	v_mfma_f32_16x16x32_bf16 v[40:43], v[156:159], v[188:191], 0
	v_mfma_f32_16x16x32_bf16 v[28:31], v[140:143], v[198:201], 0
	v_mfma_f32_16x16x32_bf16 v[24:27], v[156:159], v[198:201], 0
	v_mfma_f32_16x16x32_bf16 v[12:15], v[140:143], v[206:209], 0
	v_mfma_f32_16x16x32_bf16 v[8:11], v[156:159], v[206:209], 0
	v_mfma_f32_16x16x32_bf16 v[60:63], v[152:155], v[184:187], v[60:63]
	v_mfma_f32_16x16x32_bf16 v[56:59], v[160:163], v[184:187], v[56:59]
	v_mfma_f32_16x16x32_bf16 v[44:47], v[152:155], v[194:197], v[44:47]
	v_mfma_f32_16x16x32_bf16 v[40:43], v[160:163], v[194:197], v[40:43]
	v_mfma_f32_16x16x32_bf16 v[28:31], v[152:155], v[202:205], v[28:31]
	v_mfma_f32_16x16x32_bf16 v[24:27], v[160:163], v[202:205], v[24:27]
	v_mfma_f32_16x16x32_bf16 v[12:15], v[152:155], v[210:213], v[12:15]
	v_mfma_f32_16x16x32_bf16 v[8:11], v[160:163], v[210:213], v[8:11]
	v_mfma_f32_16x16x32_bf16 v[52:55], v[164:167], v[180:183], 0
	v_mfma_f32_16x16x32_bf16 v[48:51], v[172:175], v[180:183], 0
	v_mfma_f32_16x16x32_bf16 v[36:39], v[164:167], v[188:191], 0
	v_mfma_f32_16x16x32_bf16 v[32:35], v[172:175], v[188:191], 0
	v_mfma_f32_16x16x32_bf16 v[20:23], v[164:167], v[198:201], 0
	v_mfma_f32_16x16x32_bf16 v[16:19], v[172:175], v[198:201], 0
	v_mfma_f32_16x16x32_bf16 v[4:7], v[164:167], v[206:209], 0
	v_mfma_f32_16x16x32_bf16 v[0:3], v[172:175], v[206:209], 0
	v_mfma_f32_16x16x32_bf16 v[52:55], v[168:171], v[184:187], v[52:55]
	v_mfma_f32_16x16x32_bf16 v[48:51], v[176:179], v[184:187], v[48:51]
	v_mfma_f32_16x16x32_bf16 v[36:39], v[168:171], v[194:197], v[36:39]
	v_mfma_f32_16x16x32_bf16 v[32:35], v[176:179], v[194:197], v[32:35]
	v_mfma_f32_16x16x32_bf16 v[20:23], v[168:171], v[202:205], v[20:23]
	v_mfma_f32_16x16x32_bf16 v[16:19], v[176:179], v[202:205], v[16:19]
	v_mfma_f32_16x16x32_bf16 v[4:7], v[168:171], v[210:213], v[4:7]
	v_mfma_f32_16x16x32_bf16 v[0:3], v[176:179], v[210:213], v[0:3]
	s_barrier
	s_add_i32 s54, 0, 0x18000
	s_add_i32 s55, 0, 0x1c000
	v_add_u32_e32 v160, s54, v145
	v_add_u32_e32 v176, s55, v145
	ds_read_b128 v[140:143], v160
	ds_read_b128 v[152:155], v160 offset:1024
	ds_read_b128 v[156:159], v160 offset:2048
	ds_read_b128 v[160:163], v160 offset:3072
	ds_read_b128 v[164:167], v176
	ds_read_b128 v[168:171], v176 offset:1024
	ds_read_b128 v[172:175], v176 offset:2048
	ds_read_b128 v[176:179], v176 offset:3072
	s_add_u32 s36, s36, 0x40000
	s_addc_u32 s37, s37, 0
	s_mov_b32 m0, s21
	v_lshl_add_u64 v[222:223], s[36:37], 0, v[128:129]
	ds_read_b128 v[180:183], v151 offset:32768
	ds_read_b128 v[184:187], v151 offset:33792
	ds_read_b128 v[188:191], v151 offset:34816
	ds_read_b128 v[194:197], v151 offset:35840
	ds_read_b128 v[198:201], v151 offset:36864
	ds_read_b128 v[202:205], v151 offset:37888
	ds_read_b128 v[206:209], v151 offset:38912
	ds_read_b128 v[210:213], v151 offset:39936
	global_load_lds_dwordx4 v[222:223], off
	v_lshl_add_u64 v[222:223], s[36:37], 0, v[130:131]
	s_mov_b32 m0, s33
	s_nop 0
	global_load_lds_dwordx4 v[222:223], off
	s_waitcnt vmcnt(8)
	s_waitcnt lgkmcnt(0)
	s_barrier
	s_waitcnt lgkmcnt(0)
	v_mfma_f32_16x16x32_bf16 v[124:127], v[140:143], v[180:183], v[124:127]
	v_mfma_f32_16x16x32_bf16 v[120:123], v[156:159], v[180:183], v[120:123]
	v_mfma_f32_16x16x32_bf16 v[108:111], v[140:143], v[188:191], v[108:111]
	v_mfma_f32_16x16x32_bf16 v[104:107], v[156:159], v[188:191], v[104:107]
	v_mfma_f32_16x16x32_bf16 v[92:95], v[140:143], v[198:201], v[92:95]
	v_mfma_f32_16x16x32_bf16 v[88:91], v[156:159], v[198:201], v[88:91]
	v_mfma_f32_16x16x32_bf16 v[76:79], v[140:143], v[206:209], v[76:79]
	v_mfma_f32_16x16x32_bf16 v[72:75], v[156:159], v[206:209], v[72:75]
	v_mfma_f32_16x16x32_bf16 v[124:127], v[152:155], v[184:187], v[124:127]
	v_mfma_f32_16x16x32_bf16 v[120:123], v[160:163], v[184:187], v[120:123]
	v_mfma_f32_16x16x32_bf16 v[108:111], v[152:155], v[194:197], v[108:111]
	v_mfma_f32_16x16x32_bf16 v[104:107], v[160:163], v[194:197], v[104:107]
	v_mfma_f32_16x16x32_bf16 v[92:95], v[152:155], v[202:205], v[92:95]
	v_mfma_f32_16x16x32_bf16 v[88:91], v[160:163], v[202:205], v[88:91]
	v_mfma_f32_16x16x32_bf16 v[76:79], v[152:155], v[210:213], v[76:79]
	v_mfma_f32_16x16x32_bf16 v[72:75], v[160:163], v[210:213], v[72:75]
	v_mfma_f32_16x16x32_bf16 v[116:119], v[164:167], v[180:183], v[116:119]
	v_mfma_f32_16x16x32_bf16 v[112:115], v[172:175], v[180:183], v[112:115]
	v_mfma_f32_16x16x32_bf16 v[100:103], v[164:167], v[188:191], v[100:103]
	v_mfma_f32_16x16x32_bf16 v[96:99], v[172:175], v[188:191], v[96:99]
	v_mfma_f32_16x16x32_bf16 v[84:87], v[164:167], v[198:201], v[84:87]
	v_mfma_f32_16x16x32_bf16 v[80:83], v[172:175], v[198:201], v[80:83]
	v_mfma_f32_16x16x32_bf16 v[68:71], v[164:167], v[206:209], v[68:71]
	v_mfma_f32_16x16x32_bf16 v[64:67], v[172:175], v[206:209], v[64:67]
	v_mfma_f32_16x16x32_bf16 v[116:119], v[168:171], v[184:187], v[116:119]
	v_mfma_f32_16x16x32_bf16 v[112:115], v[176:179], v[184:187], v[112:115]
	v_mfma_f32_16x16x32_bf16 v[100:103], v[168:171], v[194:197], v[100:103]
	v_mfma_f32_16x16x32_bf16 v[96:99], v[176:179], v[194:197], v[96:99]
	v_mfma_f32_16x16x32_bf16 v[84:87], v[168:171], v[202:205], v[84:87]
	v_mfma_f32_16x16x32_bf16 v[80:83], v[176:179], v[202:205], v[80:83]
	v_mfma_f32_16x16x32_bf16 v[68:71], v[168:171], v[210:213], v[68:71]
	v_mfma_f32_16x16x32_bf16 v[64:67], v[176:179], v[210:213], v[64:67]
	s_barrier
	s_add_i32 s36, s54, s14
	v_lshl_add_u64 v[214:215], v[214:215], 0, s[8:9]
	s_mov_b32 m0, s36
	ds_read_b128 v[180:183], v151 offset:49152
	ds_read_b128 v[184:187], v151 offset:50176
	ds_read_b128 v[188:191], v151 offset:51200
	ds_read_b128 v[194:197], v151 offset:52224
	ds_read_b128 v[198:201], v151 offset:53248
	ds_read_b128 v[202:205], v151 offset:54272
	ds_read_b128 v[206:209], v151 offset:55296
	ds_read_b128 v[210:213], v151 offset:56320
	global_load_lds_dwordx4 v[214:215], off
	s_add_i32 m0, s36, 0x2000
	s_add_u32 s34, s34, 0x40080
	v_lshl_add_u64 v[214:215], v[216:217], 0, s[8:9]
	s_addc_u32 s35, s35, 0
	s_add_i32 s36, s55, s14
	global_load_lds_dwordx4 v[214:215], off
	v_lshl_add_u64 v[214:215], s[34:35], 0, v[128:129]
	s_mov_b32 m0, s36
	s_nop 0
	global_load_lds_dwordx4 v[214:215], off
	v_lshl_add_u64 v[214:215], s[34:35], 0, v[130:131]
	s_add_i32 m0, s36, 0x2000
	s_nop 0
	global_load_lds_dwordx4 v[214:215], off
	v_lshl_add_u64 v[214:215], v[218:219], 0, s[8:9]
	s_mov_b32 m0, s45
	s_nop 0
	global_load_lds_dwordx4 v[214:215], off
	v_lshl_add_u64 v[214:215], v[220:221], 0, s[8:9]
	s_mov_b32 m0, s46
	s_nop 0
	global_load_lds_dwordx4 v[214:215], off
	s_waitcnt vmcnt(8)
	s_waitcnt lgkmcnt(0)
	s_barrier
	s_waitcnt lgkmcnt(0)
	v_mfma_f32_16x16x32_bf16 v[60:63], v[140:143], v[180:183], v[60:63]
	v_mfma_f32_16x16x32_bf16 v[56:59], v[156:159], v[180:183], v[56:59]
	v_mfma_f32_16x16x32_bf16 v[44:47], v[140:143], v[188:191], v[44:47]
	v_mfma_f32_16x16x32_bf16 v[40:43], v[156:159], v[188:191], v[40:43]
	v_mfma_f32_16x16x32_bf16 v[28:31], v[140:143], v[198:201], v[28:31]
	v_mfma_f32_16x16x32_bf16 v[24:27], v[156:159], v[198:201], v[24:27]
	v_mfma_f32_16x16x32_bf16 v[12:15], v[140:143], v[206:209], v[12:15]
	v_mfma_f32_16x16x32_bf16 v[8:11], v[156:159], v[206:209], v[8:11]
	v_mfma_f32_16x16x32_bf16 v[60:63], v[152:155], v[184:187], v[60:63]
	v_mfma_f32_16x16x32_bf16 v[56:59], v[160:163], v[184:187], v[56:59]
	v_mfma_f32_16x16x32_bf16 v[44:47], v[152:155], v[194:197], v[44:47]
	v_mfma_f32_16x16x32_bf16 v[40:43], v[160:163], v[194:197], v[40:43]
	v_mfma_f32_16x16x32_bf16 v[28:31], v[152:155], v[202:205], v[28:31]
	v_mfma_f32_16x16x32_bf16 v[24:27], v[160:163], v[202:205], v[24:27]
	v_mfma_f32_16x16x32_bf16 v[12:15], v[152:155], v[210:213], v[12:15]
	v_mfma_f32_16x16x32_bf16 v[8:11], v[160:163], v[210:213], v[8:11]
	v_mfma_f32_16x16x32_bf16 v[52:55], v[164:167], v[180:183], v[52:55]
	v_mfma_f32_16x16x32_bf16 v[48:51], v[172:175], v[180:183], v[48:51]
	v_mfma_f32_16x16x32_bf16 v[36:39], v[164:167], v[188:191], v[36:39]
	v_mfma_f32_16x16x32_bf16 v[32:35], v[172:175], v[188:191], v[32:35]
	v_mfma_f32_16x16x32_bf16 v[20:23], v[164:167], v[198:201], v[20:23]
	v_mfma_f32_16x16x32_bf16 v[16:19], v[172:175], v[198:201], v[16:19]
	v_mfma_f32_16x16x32_bf16 v[4:7], v[164:167], v[206:209], v[4:7]
	v_mfma_f32_16x16x32_bf16 v[0:3], v[172:175], v[206:209], v[0:3]
	v_mfma_f32_16x16x32_bf16 v[52:55], v[168:171], v[184:187], v[52:55]
	v_mfma_f32_16x16x32_bf16 v[48:51], v[176:179], v[184:187], v[48:51]
	v_mfma_f32_16x16x32_bf16 v[36:39], v[168:171], v[194:197], v[36:39]
	v_mfma_f32_16x16x32_bf16 v[32:35], v[176:179], v[194:197], v[32:35]
	v_mfma_f32_16x16x32_bf16 v[20:23], v[168:171], v[202:205], v[20:23]
	v_mfma_f32_16x16x32_bf16 v[16:19], v[176:179], v[202:205], v[16:19]
	v_mfma_f32_16x16x32_bf16 v[4:7], v[168:171], v[210:213], v[4:7]
	v_mfma_f32_16x16x32_bf16 v[0:3], v[176:179], v[210:213], v[0:3]
	s_barrier
	s_add_i32 s53, s53, 2
	s_add_u32 s30, s30, 0x100
	s_addc_u32 s31, s31, 0
	s_add_u32 s51, s51, 0x100
	s_addc_u32 s52, s52, 0
	s_cmp_gt_u32 s53, 13
	s_cbranch_scc1 .Lpeel_x3

.Lpeel_x3:
	s_and_b64 vcc, exec, s[10:11]
	s_cbranch_vccz .LBB0_888
	s_barrier

.LBB0_973:
	s_ashr_i32 s17, s16, 31
	s_lshl_b64 s[18:19], s[16:17], 19
	s_add_u32 s18, s82, s18
	s_addc_u32 s19, s83, s19
	s_and_b64 s[20:21], s[40:41], exec
	s_cselect_b32 s17, s19, s27
	s_cselect_b32 s47, s18, s26
	s_ashr_i32 s13, s12, 31
	s_lshl_b64 s[20:21], s[12:13], 19
	s_add_u32 s20, s58, s20
	s_addc_u32 s21, s59, s21
	s_and_b64 s[30:31], s[40:41], exec
	s_cselect_b32 s13, s21, s29
	s_cselect_b32 s48, s20, s28
	s_add_u32 s26, s26, 0x40080
	s_addc_u32 s27, s27, 0
	s_add_u32 s49, s28, 0x100
	s_addc_u32 s50, s29, 0
	s_mov_b32 s51, -2
	ds_read_b128 v[154:157], v150
	ds_read_b128 v[158:161], v150 offset:1024
	ds_read_b128 v[162:165], v150 offset:2048
	ds_read_b128 v[166:169], v150 offset:3072
	ds_read_b128 v[170:173], v151
	ds_read_b128 v[174:177], v151 offset:1024
	ds_read_b128 v[178:181], v151 offset:2048
	ds_read_b128 v[182:185], v151 offset:3072
	s_add_u32 s28, s26, 0xfffc0080
	s_addc_u32 s29, s27, -1
	s_cmp_eq_u32 s51, 12
	s_cselect_b32 s31, s17, s29
	s_cselect_b32 s30, s47, s28
	s_cselect_b32 s29, s13, s50
	s_cselect_b32 s28, s48, s49
	v_lshl_add_u64 v[146:147], s[26:27], 0, v[138:139]
	s_add_i32 m0, s33, 0xc000
	ds_read_b128 v[186:189], v152
	ds_read_b128 v[194:197], v152 offset:1024
	ds_read_b128 v[198:201], v152 offset:2048
	ds_read_b128 v[202:205], v152 offset:3072
	ds_read_b128 v[206:209], v152 offset:4096
	ds_read_b128 v[210:213], v152 offset:5120
	ds_read_b128 v[214:217], v152 offset:6144
	ds_read_b128 v[218:221], v152 offset:7168
	global_load_lds_dwordx4 v[146:147], off
	v_lshl_add_u64 v[146:147], s[26:27], 0, v[140:141]
	s_add_i32 m0, s33, 0xe000
	s_nop 0
	global_load_lds_dwordx4 v[146:147], off
	s_waitcnt vmcnt(8)
	s_waitcnt lgkmcnt(0)
	s_barrier
	s_waitcnt lgkmcnt(0)
	v_mfma_f32_16x16x32_bf16 v[124:127], v[154:157], v[186:189], 0
	v_mfma_f32_16x16x32_bf16 v[120:123], v[162:165], v[186:189], 0
	v_mfma_f32_16x16x32_bf16 v[108:111], v[154:157], v[198:201], 0
	v_mfma_f32_16x16x32_bf16 v[104:107], v[162:165], v[198:201], 0
	v_mfma_f32_16x16x32_bf16 v[92:95], v[154:157], v[206:209], 0
	v_mfma_f32_16x16x32_bf16 v[88:91], v[162:165], v[206:209], 0
	v_mfma_f32_16x16x32_bf16 v[76:79], v[154:157], v[214:217], 0
	v_mfma_f32_16x16x32_bf16 v[72:75], v[162:165], v[214:217], 0
	v_mfma_f32_16x16x32_bf16 v[124:127], v[158:161], v[194:197], v[124:127]
	v_mfma_f32_16x16x32_bf16 v[120:123], v[166:169], v[194:197], v[120:123]
	v_mfma_f32_16x16x32_bf16 v[108:111], v[158:161], v[202:205], v[108:111]
	v_mfma_f32_16x16x32_bf16 v[104:107], v[166:169], v[202:205], v[104:107]
	v_mfma_f32_16x16x32_bf16 v[92:95], v[158:161], v[210:213], v[92:95]
	v_mfma_f32_16x16x32_bf16 v[88:91], v[166:169], v[210:213], v[88:91]
	v_mfma_f32_16x16x32_bf16 v[76:79], v[158:161], v[218:221], v[76:79]
	v_mfma_f32_16x16x32_bf16 v[72:75], v[166:169], v[218:221], v[72:75]
	v_mfma_f32_16x16x32_bf16 v[116:119], v[170:173], v[186:189], 0
	v_mfma_f32_16x16x32_bf16 v[112:115], v[178:181], v[186:189], 0
	v_mfma_f32_16x16x32_bf16 v[100:103], v[170:173], v[198:201], 0
	v_mfma_f32_16x16x32_bf16 v[96:99], v[178:181], v[198:201], 0
	v_mfma_f32_16x16x32_bf16 v[84:87], v[170:173], v[206:209], 0
	v_mfma_f32_16x16x32_bf16 v[80:83], v[178:181], v[206:209], 0
	v_mfma_f32_16x16x32_bf16 v[68:71], v[170:173], v[214:217], 0
	v_mfma_f32_16x16x32_bf16 v[64:67], v[178:181], v[214:217], 0
	v_mfma_f32_16x16x32_bf16 v[116:119], v[174:177], v[194:197], v[116:119]
	v_mfma_f32_16x16x32_bf16 v[112:115], v[182:185], v[194:197], v[112:115]
	v_mfma_f32_16x16x32_bf16 v[100:103], v[174:177], v[202:205], v[100:103]
	v_mfma_f32_16x16x32_bf16 v[96:99], v[182:185], v[202:205], v[96:99]
	v_mfma_f32_16x16x32_bf16 v[84:87], v[174:177], v[210:213], v[84:87]
	v_mfma_f32_16x16x32_bf16 v[80:83], v[182:185], v[210:213], v[80:83]
	v_mfma_f32_16x16x32_bf16 v[68:71], v[174:177], v[218:221], v[68:71]
	v_mfma_f32_16x16x32_bf16 v[64:67], v[182:185], v[218:221], v[64:67]
	s_barrier
	s_add_i32 s52, s43, s14
	v_lshl_add_u64 v[146:147], s[28:29], 0, v[132:133]
	s_mov_b32 m0, s52
	ds_read_b128 v[186:189], v152 offset:16384
	ds_read_b128 v[194:197], v152 offset:17408
	ds_read_b128 v[198:201], v152 offset:18432
	ds_read_b128 v[202:205], v152 offset:19456
	ds_read_b128 v[206:209], v152 offset:20480
	ds_read_b128 v[210:213], v152 offset:21504
	ds_read_b128 v[214:217], v152 offset:22528
	ds_read_b128 v[218:221], v152 offset:23552
	global_load_lds_dwordx4 v[146:147], off
	s_add_i32 m0, s52, 0x2000
	s_add_u32 s52, s28, 0x40000
	v_lshl_add_u64 v[190:191], s[28:29], 0, v[128:129]
	s_addc_u32 s53, s29, 0
	s_add_i32 s54, s44, s14
	global_load_lds_dwordx4 v[190:191], off
	v_lshl_add_u64 v[222:223], s[52:53], 0, v[132:133]
	s_mov_b32 m0, s54
	v_lshl_add_u64 v[224:225], s[30:31], 0, v[130:131]
	global_load_lds_dwordx4 v[222:223], off
	v_lshl_add_u64 v[222:223], s[52:53], 0, v[128:129]
	s_add_i32 m0, s54, 0x2000
	s_nop 0
	global_load_lds_dwordx4 v[222:223], off
	v_lshl_add_u64 v[222:223], s[30:31], 0, v[134:135]
	s_mov_b32 m0, s33
	s_nop 0
	global_load_lds_dwordx4 v[222:223], off
	s_mov_b32 m0, s34
	s_nop 0
	global_load_lds_dwordx4 v[224:225], off
	s_waitcnt vmcnt(8)
	s_waitcnt lgkmcnt(0)
	s_barrier
	s_waitcnt lgkmcnt(0)
	v_mfma_f32_16x16x32_bf16 v[60:63], v[154:157], v[186:189], 0
	v_mfma_f32_16x16x32_bf16 v[56:59], v[162:165], v[186:189], 0
	v_mfma_f32_16x16x32_bf16 v[44:47], v[154:157], v[198:201], 0
	v_mfma_f32_16x16x32_bf16 v[40:43], v[162:165], v[198:201], 0
	v_mfma_f32_16x16x32_bf16 v[28:31], v[154:157], v[206:209], 0
	v_mfma_f32_16x16x32_bf16 v[24:27], v[162:165], v[206:209], 0
	v_mfma_f32_16x16x32_bf16 v[12:15], v[154:157], v[214:217], 0
	v_mfma_f32_16x16x32_bf16 v[8:11], v[162:165], v[214:217], 0
	v_mfma_f32_16x16x32_bf16 v[60:63], v[158:161], v[194:197], v[60:63]
	v_mfma_f32_16x16x32_bf16 v[56:59], v[166:169], v[194:197], v[56:59]
	v_mfma_f32_16x16x32_bf16 v[44:47], v[158:161], v[202:205], v[44:47]
	v_mfma_f32_16x16x32_bf16 v[40:43], v[166:169], v[202:205], v[40:43]
	v_mfma_f32_16x16x32_bf16 v[28:31], v[158:161], v[210:213], v[28:31]
	v_mfma_f32_16x16x32_bf16 v[24:27], v[166:169], v[210:213], v[24:27]
	v_mfma_f32_16x16x32_bf16 v[12:15], v[158:161], v[218:221], v[12:15]
	v_mfma_f32_16x16x32_bf16 v[8:11], v[166:169], v[218:221], v[8:11]
	v_mfma_f32_16x16x32_bf16 v[52:55], v[170:173], v[186:189], 0
	v_mfma_f32_16x16x32_bf16 v[48:51], v[178:181], v[186:189], 0
	v_mfma_f32_16x16x32_bf16 v[36:39], v[170:173], v[198:201], 0
	v_mfma_f32_16x16x32_bf16 v[32:35], v[178:181], v[198:201], 0
	v_mfma_f32_16x16x32_bf16 v[20:23], v[170:173], v[206:209], 0
	v_mfma_f32_16x16x32_bf16 v[16:19], v[178:181], v[206:209], 0
	v_mfma_f32_16x16x32_bf16 v[4:7], v[170:173], v[214:217], 0
	v_mfma_f32_16x16x32_bf16 v[0:3], v[178:181], v[214:217], 0
	v_mfma_f32_16x16x32_bf16 v[52:55], v[174:177], v[194:197], v[52:55]
	v_mfma_f32_16x16x32_bf16 v[48:51], v[182:185], v[194:197], v[48:51]
	v_mfma_f32_16x16x32_bf16 v[36:39], v[174:177], v[202:205], v[36:39]
	v_mfma_f32_16x16x32_bf16 v[32:35], v[182:185], v[202:205], v[32:35]
	v_mfma_f32_16x16x32_bf16 v[20:23], v[174:177], v[210:213], v[20:23]
	v_mfma_f32_16x16x32_bf16 v[16:19], v[182:185], v[210:213], v[16:19]
	v_mfma_f32_16x16x32_bf16 v[4:7], v[174:177], v[218:221], v[4:7]
	v_mfma_f32_16x16x32_bf16 v[0:3], v[182:185], v[218:221], v[0:3]
	s_barrier
	s_add_i32 s52, 0, 0x18000
	s_add_i32 s53, 0, 0x1c000
	v_add_u32_e32 v166, s52, v149
	v_add_u32_e32 v182, s53, v149
	ds_read_b128 v[154:157], v166
	ds_read_b128 v[158:161], v166 offset:1024
	ds_read_b128 v[162:165], v166 offset:2048
	ds_read_b128 v[166:169], v166 offset:3072
	ds_read_b128 v[170:173], v182
	ds_read_b128 v[174:177], v182 offset:1024
	ds_read_b128 v[178:181], v182 offset:2048
	ds_read_b128 v[182:185], v182 offset:3072
	s_add_u32 s30, s30, 0x40000
	s_addc_u32 s31, s31, 0
	s_mov_b32 m0, s35
	v_lshl_add_u64 v[226:227], s[30:31], 0, v[134:135]
	ds_read_b128 v[186:189], v152 offset:32768
	ds_read_b128 v[194:197], v152 offset:33792
	ds_read_b128 v[198:201], v152 offset:34816
	ds_read_b128 v[202:205], v152 offset:35840
	ds_read_b128 v[206:209], v152 offset:36864
	ds_read_b128 v[210:213], v152 offset:37888
	ds_read_b128 v[214:217], v152 offset:38912
	ds_read_b128 v[218:221], v152 offset:39936
	global_load_lds_dwordx4 v[226:227], off
	v_lshl_add_u64 v[226:227], s[30:31], 0, v[130:131]
	s_mov_b32 m0, s36
	s_nop 0
	global_load_lds_dwordx4 v[226:227], off
	s_waitcnt vmcnt(8)
	s_waitcnt lgkmcnt(0)
	s_barrier
	s_waitcnt lgkmcnt(0)
	v_mfma_f32_16x16x32_bf16 v[124:127], v[154:157], v[186:189], v[124:127]
	v_mfma_f32_16x16x32_bf16 v[120:123], v[162:165], v[186:189], v[120:123]
	v_mfma_f32_16x16x32_bf16 v[108:111], v[154:157], v[198:201], v[108:111]
	v_mfma_f32_16x16x32_bf16 v[104:107], v[162:165], v[198:201], v[104:107]
	v_mfma_f32_16x16x32_bf16 v[92:95], v[154:157], v[206:209], v[92:95]
	v_mfma_f32_16x16x32_bf16 v[88:91], v[162:165], v[206:209], v[88:91]
	v_mfma_f32_16x16x32_bf16 v[76:79], v[154:157], v[214:217], v[76:79]
	v_mfma_f32_16x16x32_bf16 v[72:75], v[162:165], v[214:217], v[72:75]
	v_mfma_f32_16x16x32_bf16 v[124:127], v[158:161], v[194:197], v[124:127]
	v_mfma_f32_16x16x32_bf16 v[120:123], v[166:169], v[194:197], v[120:123]
	v_mfma_f32_16x16x32_bf16 v[108:111], v[158:161], v[202:205], v[108:111]
	v_mfma_f32_16x16x32_bf16 v[104:107], v[166:169], v[202:205], v[104:107]
	v_mfma_f32_16x16x32_bf16 v[92:95], v[158:161], v[210:213], v[92:95]
	v_mfma_f32_16x16x32_bf16 v[88:91], v[166:169], v[210:213], v[88:91]
	v_mfma_f32_16x16x32_bf16 v[76:79], v[158:161], v[218:221], v[76:79]
	v_mfma_f32_16x16x32_bf16 v[72:75], v[166:169], v[218:221], v[72:75]
	v_mfma_f32_16x16x32_bf16 v[116:119], v[170:173], v[186:189], v[116:119]
	v_mfma_f32_16x16x32_bf16 v[112:115], v[178:181], v[186:189], v[112:115]
	v_mfma_f32_16x16x32_bf16 v[100:103], v[170:173], v[198:201], v[100:103]
	v_mfma_f32_16x16x32_bf16 v[96:99], v[178:181], v[198:201], v[96:99]
	v_mfma_f32_16x16x32_bf16 v[84:87], v[170:173], v[206:209], v[84:87]
	v_mfma_f32_16x16x32_bf16 v[80:83], v[178:181], v[206:209], v[80:83]
	v_mfma_f32_16x16x32_bf16 v[68:71], v[170:173], v[214:217], v[68:71]
	v_mfma_f32_16x16x32_bf16 v[64:67], v[178:181], v[214:217], v[64:67]
	v_mfma_f32_16x16x32_bf16 v[116:119], v[174:177], v[194:197], v[116:119]
	v_mfma_f32_16x16x32_bf16 v[112:115], v[182:185], v[194:197], v[112:115]
	v_mfma_f32_16x16x32_bf16 v[100:103], v[174:177], v[202:205], v[100:103]
	v_mfma_f32_16x16x32_bf16 v[96:99], v[182:185], v[202:205], v[96:99]
	v_mfma_f32_16x16x32_bf16 v[84:87], v[174:177], v[210:213], v[84:87]
	v_mfma_f32_16x16x32_bf16 v[80:83], v[182:185], v[210:213], v[80:83]
	v_mfma_f32_16x16x32_bf16 v[68:71], v[174:177], v[218:221], v[68:71]
	v_mfma_f32_16x16x32_bf16 v[64:67], v[182:185], v[218:221], v[64:67]
	s_barrier
	s_add_i32 s30, s52, s14
	v_lshl_add_u64 v[146:147], v[146:147], 0, s[6:7]
	s_mov_b32 m0, s30
	ds_read_b128 v[186:189], v152 offset:49152
	ds_read_b128 v[194:197], v152 offset:50176
	ds_read_b128 v[198:201], v152 offset:51200
	ds_read_b128 v[202:205], v152 offset:52224
	ds_read_b128 v[206:209], v152 offset:53248
	ds_read_b128 v[210:213], v152 offset:54272
	ds_read_b128 v[214:217], v152 offset:55296
	ds_read_b128 v[218:221], v152 offset:56320
	global_load_lds_dwordx4 v[146:147], off
	s_add_i32 m0, s30, 0x2000
	s_add_u32 s28, s28, 0x40080
	v_lshl_add_u64 v[146:147], v[190:191], 0, s[6:7]
	s_addc_u32 s29, s29, 0
	s_add_i32 s30, s53, s14
	global_load_lds_dwordx4 v[146:147], off
	v_lshl_add_u64 v[146:147], s[28:29], 0, v[132:133]
	s_mov_b32 m0, s30
	s_nop 0
	global_load_lds_dwordx4 v[146:147], off
	v_lshl_add_u64 v[146:147], s[28:29], 0, v[128:129]
	s_add_i32 m0, s30, 0x2000
	s_nop 0
	global_load_lds_dwordx4 v[146:147], off
	v_lshl_add_u64 v[146:147], v[222:223], 0, s[6:7]
	s_mov_b32 m0, s37
	s_nop 0
	global_load_lds_dwordx4 v[146:147], off
	v_lshl_add_u64 v[146:147], v[224:225], 0, s[6:7]
	s_mov_b32 m0, s42
	s_nop 0
	global_load_lds_dwordx4 v[146:147], off
	s_waitcnt vmcnt(8)
	s_waitcnt lgkmcnt(0)
	s_barrier
	s_waitcnt lgkmcnt(0)
	v_mfma_f32_16x16x32_bf16 v[60:63], v[154:157], v[186:189], v[60:63]
	v_mfma_f32_16x16x32_bf16 v[56:59], v[162:165], v[186:189], v[56:59]
	v_mfma_f32_16x16x32_bf16 v[44:47], v[154:157], v[198:201], v[44:47]
	v_mfma_f32_16x16x32_bf16 v[40:43], v[162:165], v[198:201], v[40:43]
	v_mfma_f32_16x16x32_bf16 v[28:31], v[154:157], v[206:209], v[28:31]
	v_mfma_f32_16x16x32_bf16 v[24:27], v[162:165], v[206:209], v[24:27]
	v_mfma_f32_16x16x32_bf16 v[12:15], v[154:157], v[214:217], v[12:15]
	v_mfma_f32_16x16x32_bf16 v[8:11], v[162:165], v[214:217], v[8:11]
	v_mfma_f32_16x16x32_bf16 v[60:63], v[158:161], v[194:197], v[60:63]
	v_mfma_f32_16x16x32_bf16 v[56:59], v[166:169], v[194:197], v[56:59]
	v_mfma_f32_16x16x32_bf16 v[44:47], v[158:161], v[202:205], v[44:47]
	v_mfma_f32_16x16x32_bf16 v[40:43], v[166:169], v[202:205], v[40:43]
	v_mfma_f32_16x16x32_bf16 v[28:31], v[158:161], v[210:213], v[28:31]
	v_mfma_f32_16x16x32_bf16 v[24:27], v[166:169], v[210:213], v[24:27]
	v_mfma_f32_16x16x32_bf16 v[12:15], v[158:161], v[218:221], v[12:15]
	v_mfma_f32_16x16x32_bf16 v[8:11], v[166:169], v[218:221], v[8:11]
	v_mfma_f32_16x16x32_bf16 v[52:55], v[170:173], v[186:189], v[52:55]
	v_mfma_f32_16x16x32_bf16 v[48:51], v[178:181], v[186:189], v[48:51]
	v_mfma_f32_16x16x32_bf16 v[36:39], v[170:173], v[198:201], v[36:39]
	v_mfma_f32_16x16x32_bf16 v[32:35], v[178:181], v[198:201], v[32:35]
	v_mfma_f32_16x16x32_bf16 v[20:23], v[170:173], v[206:209], v[20:23]
	v_mfma_f32_16x16x32_bf16 v[16:19], v[178:181], v[206:209], v[16:19]
	v_mfma_f32_16x16x32_bf16 v[4:7], v[170:173], v[214:217], v[4:7]
	v_mfma_f32_16x16x32_bf16 v[0:3], v[178:181], v[214:217], v[0:3]
	v_mfma_f32_16x16x32_bf16 v[52:55], v[174:177], v[194:197], v[52:55]
	v_mfma_f32_16x16x32_bf16 v[48:51], v[182:185], v[194:197], v[48:51]
	v_mfma_f32_16x16x32_bf16 v[36:39], v[174:177], v[202:205], v[36:39]
	v_mfma_f32_16x16x32_bf16 v[32:35], v[182:185], v[202:205], v[32:35]
	v_mfma_f32_16x16x32_bf16 v[20:23], v[174:177], v[210:213], v[20:23]
	v_mfma_f32_16x16x32_bf16 v[16:19], v[182:185], v[210:213], v[16:19]
	v_mfma_f32_16x16x32_bf16 v[4:7], v[174:177], v[218:221], v[4:7]
	v_mfma_f32_16x16x32_bf16 v[0:3], v[182:185], v[218:221], v[0:3]
	s_barrier
	s_add_i32 s51, s51, 2
	s_add_u32 s26, s26, 0x100
	s_addc_u32 s27, s27, 0
	s_add_u32 s49, s49, 0x100
	s_addc_u32 s50, s50, 0
	s_cmp_gt_u32 s51, 13
	s_cbranch_scc1 .Lpeel_x4

.LBB0_1054:
	s_add_u32 s37, s16, 0x100
	s_addc_u32 s38, s17, 0
	s_mov_b32 s39, -2
	ds_read_b128 v[142:145], v147
	ds_read_b128 v[150:153], v147 offset:1024
	ds_read_b128 v[154:157], v147 offset:2048
	ds_read_b128 v[158:161], v147 offset:3072
	ds_read_b128 v[162:165], v148
	ds_read_b128 v[166:169], v148 offset:1024
	ds_read_b128 v[170:173], v148 offset:2048
	ds_read_b128 v[174:177], v148 offset:3072
	s_add_u32 s16, s14, 0x100
	s_addc_u32 s17, s15, 0
	s_cmp_eq_u32 s39, 40
	s_cselect_b32 s21, s5, s17
	s_cselect_b32 s20, s4, s16
	s_cselect_b32 s19, s13, s38
	s_cselect_b32 s18, s12, s37
	v_lshl_add_u64 v[210:211], s[14:15], 0, v[134:135]
	s_add_i32 m0, s23, 0xc000
	ds_read_b128 v[178:181], v149
	ds_read_b128 v[182:185], v149 offset:1024
	ds_read_b128 v[186:189], v149 offset:2048
	ds_read_b128 v[190:193], v149 offset:3072
	ds_read_b128 v[194:197], v149 offset:4096
	ds_read_b128 v[198:201], v149 offset:5120
	ds_read_b128 v[202:205], v149 offset:6144
	ds_read_b128 v[206:209], v149 offset:7168
	global_load_lds_dwordx4 v[210:211], off
	v_lshl_add_u64 v[210:211], s[14:15], 0, v[136:137]
	s_add_i32 m0, s23, 0xe000
	s_nop 0
	global_load_lds_dwordx4 v[210:211], off
	s_waitcnt vmcnt(8)
	s_waitcnt lgkmcnt(0)
	s_barrier
	s_waitcnt lgkmcnt(0)
	v_mfma_f32_16x16x32_bf16 v[124:127], v[142:145], v[178:181], 0
	v_mfma_f32_16x16x32_bf16 v[120:123], v[154:157], v[178:181], 0
	v_mfma_f32_16x16x32_bf16 v[108:111], v[142:145], v[186:189], 0
	v_mfma_f32_16x16x32_bf16 v[104:107], v[154:157], v[186:189], 0
	v_mfma_f32_16x16x32_bf16 v[92:95], v[142:145], v[194:197], 0
	v_mfma_f32_16x16x32_bf16 v[88:91], v[154:157], v[194:197], 0
	v_mfma_f32_16x16x32_bf16 v[76:79], v[142:145], v[202:205], 0
	v_mfma_f32_16x16x32_bf16 v[72:75], v[154:157], v[202:205], 0
	v_mfma_f32_16x16x32_bf16 v[124:127], v[150:153], v[182:185], v[124:127]
	v_mfma_f32_16x16x32_bf16 v[120:123], v[158:161], v[182:185], v[120:123]
	v_mfma_f32_16x16x32_bf16 v[108:111], v[150:153], v[190:193], v[108:111]
	v_mfma_f32_16x16x32_bf16 v[104:107], v[158:161], v[190:193], v[104:107]
	v_mfma_f32_16x16x32_bf16 v[92:95], v[150:153], v[198:201], v[92:95]
	v_mfma_f32_16x16x32_bf16 v[88:91], v[158:161], v[198:201], v[88:91]
	v_mfma_f32_16x16x32_bf16 v[76:79], v[150:153], v[206:209], v[76:79]
	v_mfma_f32_16x16x32_bf16 v[72:75], v[158:161], v[206:209], v[72:75]
	v_mfma_f32_16x16x32_bf16 v[116:119], v[162:165], v[178:181], 0
	v_mfma_f32_16x16x32_bf16 v[112:115], v[170:173], v[178:181], 0
	v_mfma_f32_16x16x32_bf16 v[100:103], v[162:165], v[186:189], 0
	v_mfma_f32_16x16x32_bf16 v[96:99], v[170:173], v[186:189], 0
	v_mfma_f32_16x16x32_bf16 v[84:87], v[162:165], v[194:197], 0
	v_mfma_f32_16x16x32_bf16 v[80:83], v[170:173], v[194:197], 0
	v_mfma_f32_16x16x32_bf16 v[68:71], v[162:165], v[202:205], 0
	v_mfma_f32_16x16x32_bf16 v[64:67], v[170:173], v[202:205], 0
	v_mfma_f32_16x16x32_bf16 v[116:119], v[166:169], v[182:185], v[116:119]
	v_mfma_f32_16x16x32_bf16 v[112:115], v[174:177], v[182:185], v[112:115]
	v_mfma_f32_16x16x32_bf16 v[100:103], v[166:169], v[190:193], v[100:103]
	v_mfma_f32_16x16x32_bf16 v[96:99], v[174:177], v[190:193], v[96:99]
	v_mfma_f32_16x16x32_bf16 v[84:87], v[166:169], v[198:201], v[84:87]
	v_mfma_f32_16x16x32_bf16 v[80:83], v[174:177], v[198:201], v[80:83]
	v_mfma_f32_16x16x32_bf16 v[68:71], v[166:169], v[206:209], v[68:71]
	v_mfma_f32_16x16x32_bf16 v[64:67], v[174:177], v[206:209], v[64:67]
	s_barrier
	s_add_i32 s14, s30, s22
	v_lshl_add_u64 v[210:211], s[18:19], 0, v[130:131]
	s_mov_b32 m0, s14
	ds_read_b128 v[178:181], v149 offset:16384
	ds_read_b128 v[182:185], v149 offset:17408
	ds_read_b128 v[186:189], v149 offset:18432
	ds_read_b128 v[190:193], v149 offset:19456
	ds_read_b128 v[194:197], v149 offset:20480
	ds_read_b128 v[198:201], v149 offset:21504
	ds_read_b128 v[202:205], v149 offset:22528
	ds_read_b128 v[206:209], v149 offset:23552
	global_load_lds_dwordx4 v[210:211], off
	s_add_i32 m0, s14, 0x2000
	s_add_u32 s14, s18, 0xb0000
	v_lshl_add_u64 v[212:213], s[18:19], 0, v[128:129]
	s_addc_u32 s15, s19, 0
	s_add_i32 s40, s31, s22
	global_load_lds_dwordx4 v[212:213], off
	v_lshl_add_u64 v[214:215], s[14:15], 0, v[130:131]
	s_mov_b32 m0, s40
	v_lshl_add_u64 v[216:217], s[20:21], 0, v[128:129]
	global_load_lds_dwordx4 v[214:215], off
	v_lshl_add_u64 v[214:215], s[14:15], 0, v[128:129]
	s_add_i32 m0, s40, 0x2000
	s_nop 0
	global_load_lds_dwordx4 v[214:215], off
	v_lshl_add_u64 v[214:215], s[20:21], 0, v[130:131]
	s_mov_b32 m0, s23
	s_nop 0
	global_load_lds_dwordx4 v[214:215], off
	s_mov_b32 m0, s24
	s_nop 0
	global_load_lds_dwordx4 v[216:217], off
	s_waitcnt vmcnt(8)
	s_waitcnt lgkmcnt(0)
	s_barrier
	s_waitcnt lgkmcnt(0)
	v_mfma_f32_16x16x32_bf16 v[60:63], v[142:145], v[178:181], 0
	v_mfma_f32_16x16x32_bf16 v[56:59], v[154:157], v[178:181], 0
	v_mfma_f32_16x16x32_bf16 v[44:47], v[142:145], v[186:189], 0
	v_mfma_f32_16x16x32_bf16 v[40:43], v[154:157], v[186:189], 0
	v_mfma_f32_16x16x32_bf16 v[28:31], v[142:145], v[194:197], 0
	v_mfma_f32_16x16x32_bf16 v[24:27], v[154:157], v[194:197], 0
	v_mfma_f32_16x16x32_bf16 v[12:15], v[142:145], v[202:205], 0
	v_mfma_f32_16x16x32_bf16 v[8:11], v[154:157], v[202:205], 0
	v_mfma_f32_16x16x32_bf16 v[60:63], v[150:153], v[182:185], v[60:63]
	v_mfma_f32_16x16x32_bf16 v[56:59], v[158:161], v[182:185], v[56:59]
	v_mfma_f32_16x16x32_bf16 v[44:47], v[150:153], v[190:193], v[44:47]
	v_mfma_f32_16x16x32_bf16 v[40:43], v[158:161], v[190:193], v[40:43]
	v_mfma_f32_16x16x32_bf16 v[28:31], v[150:153], v[198:201], v[28:31]
	v_mfma_f32_16x16x32_bf16 v[24:27], v[158:161], v[198:201], v[24:27]
	v_mfma_f32_16x16x32_bf16 v[12:15], v[150:153], v[206:209], v[12:15]
	v_mfma_f32_16x16x32_bf16 v[8:11], v[158:161], v[206:209], v[8:11]
	v_mfma_f32_16x16x32_bf16 v[52:55], v[162:165], v[178:181], 0
	v_mfma_f32_16x16x32_bf16 v[48:51], v[170:173], v[178:181], 0
	v_mfma_f32_16x16x32_bf16 v[36:39], v[162:165], v[186:189], 0
	v_mfma_f32_16x16x32_bf16 v[32:35], v[170:173], v[186:189], 0
	v_mfma_f32_16x16x32_bf16 v[20:23], v[162:165], v[194:197], 0
	v_mfma_f32_16x16x32_bf16 v[16:19], v[170:173], v[194:197], 0
	v_mfma_f32_16x16x32_bf16 v[4:7], v[162:165], v[202:205], 0
	v_mfma_f32_16x16x32_bf16 v[0:3], v[170:173], v[202:205], 0
	v_mfma_f32_16x16x32_bf16 v[52:55], v[166:169], v[182:185], v[52:55]
	v_mfma_f32_16x16x32_bf16 v[48:51], v[174:177], v[182:185], v[48:51]
	v_mfma_f32_16x16x32_bf16 v[36:39], v[166:169], v[190:193], v[36:39]
	v_mfma_f32_16x16x32_bf16 v[32:35], v[174:177], v[190:193], v[32:35]
	v_mfma_f32_16x16x32_bf16 v[20:23], v[166:169], v[198:201], v[20:23]
	v_mfma_f32_16x16x32_bf16 v[16:19], v[174:177], v[198:201], v[16:19]
	v_mfma_f32_16x16x32_bf16 v[4:7], v[166:169], v[206:209], v[4:7]
	v_mfma_f32_16x16x32_bf16 v[0:3], v[174:177], v[206:209], v[0:3]
	s_barrier
	s_add_i32 s40, 0, 0x18000
	s_add_i32 s41, 0, 0x1c000
	v_add_u32_e32 v158, s40, v146
	v_add_u32_e32 v174, s41, v146
	ds_read_b128 v[142:145], v158
	ds_read_b128 v[150:153], v158 offset:1024
	ds_read_b128 v[154:157], v158 offset:2048
	ds_read_b128 v[158:161], v158 offset:3072
	ds_read_b128 v[162:165], v174
	ds_read_b128 v[166:169], v174 offset:1024
	ds_read_b128 v[170:173], v174 offset:2048
	ds_read_b128 v[174:177], v174 offset:3072
	s_add_u32 s14, s20, 0xb0000
	s_addc_u32 s15, s21, 0
	s_mov_b32 m0, s25
	v_lshl_add_u64 v[218:219], s[14:15], 0, v[130:131]
	ds_read_b128 v[178:181], v149 offset:32768
	ds_read_b128 v[182:185], v149 offset:33792
	ds_read_b128 v[186:189], v149 offset:34816
	ds_read_b128 v[190:193], v149 offset:35840
	ds_read_b128 v[194:197], v149 offset:36864
	ds_read_b128 v[198:201], v149 offset:37888
	ds_read_b128 v[202:205], v149 offset:38912
	ds_read_b128 v[206:209], v149 offset:39936
	global_load_lds_dwordx4 v[218:219], off
	v_lshl_add_u64 v[218:219], s[14:15], 0, v[128:129]
	s_mov_b32 m0, s26
	s_nop 0
	global_load_lds_dwordx4 v[218:219], off
	s_waitcnt vmcnt(8)
	s_waitcnt lgkmcnt(0)
	s_barrier
	s_waitcnt lgkmcnt(0)
	v_mfma_f32_16x16x32_bf16 v[124:127], v[142:145], v[178:181], v[124:127]
	v_mfma_f32_16x16x32_bf16 v[120:123], v[154:157], v[178:181], v[120:123]
	v_mfma_f32_16x16x32_bf16 v[108:111], v[142:145], v[186:189], v[108:111]
	v_mfma_f32_16x16x32_bf16 v[104:107], v[154:157], v[186:189], v[104:107]
	v_mfma_f32_16x16x32_bf16 v[92:95], v[142:145], v[194:197], v[92:95]
	v_mfma_f32_16x16x32_bf16 v[88:91], v[154:157], v[194:197], v[88:91]
	v_mfma_f32_16x16x32_bf16 v[76:79], v[142:145], v[202:205], v[76:79]
	v_mfma_f32_16x16x32_bf16 v[72:75], v[154:157], v[202:205], v[72:75]
	v_mfma_f32_16x16x32_bf16 v[124:127], v[150:153], v[182:185], v[124:127]
	v_mfma_f32_16x16x32_bf16 v[120:123], v[158:161], v[182:185], v[120:123]
	v_mfma_f32_16x16x32_bf16 v[108:111], v[150:153], v[190:193], v[108:111]
	v_mfma_f32_16x16x32_bf16 v[104:107], v[158:161], v[190:193], v[104:107]
	v_mfma_f32_16x16x32_bf16 v[92:95], v[150:153], v[198:201], v[92:95]
	v_mfma_f32_16x16x32_bf16 v[88:91], v[158:161], v[198:201], v[88:91]
	v_mfma_f32_16x16x32_bf16 v[76:79], v[150:153], v[206:209], v[76:79]
	v_mfma_f32_16x16x32_bf16 v[72:75], v[158:161], v[206:209], v[72:75]
	v_mfma_f32_16x16x32_bf16 v[116:119], v[162:165], v[178:181], v[116:119]
	v_mfma_f32_16x16x32_bf16 v[112:115], v[170:173], v[178:181], v[112:115]
	v_mfma_f32_16x16x32_bf16 v[100:103], v[162:165], v[186:189], v[100:103]
	v_mfma_f32_16x16x32_bf16 v[96:99], v[170:173], v[186:189], v[96:99]
	v_mfma_f32_16x16x32_bf16 v[84:87], v[162:165], v[194:197], v[84:87]
	v_mfma_f32_16x16x32_bf16 v[80:83], v[170:173], v[194:197], v[80:83]
	v_mfma_f32_16x16x32_bf16 v[68:71], v[162:165], v[202:205], v[68:71]
	v_mfma_f32_16x16x32_bf16 v[64:67], v[170:173], v[202:205], v[64:67]
	v_mfma_f32_16x16x32_bf16 v[116:119], v[166:169], v[182:185], v[116:119]
	v_mfma_f32_16x16x32_bf16 v[112:115], v[174:177], v[182:185], v[112:115]
	v_mfma_f32_16x16x32_bf16 v[100:103], v[166:169], v[190:193], v[100:103]
	v_mfma_f32_16x16x32_bf16 v[96:99], v[174:177], v[190:193], v[96:99]
	v_mfma_f32_16x16x32_bf16 v[84:87], v[166:169], v[198:201], v[84:87]
	v_mfma_f32_16x16x32_bf16 v[80:83], v[174:177], v[198:201], v[80:83]
	v_mfma_f32_16x16x32_bf16 v[68:71], v[166:169], v[206:209], v[68:71]
	v_mfma_f32_16x16x32_bf16 v[64:67], v[174:177], v[206:209], v[64:67]
	s_barrier
	s_add_i32 s14, s40, s22
	v_lshl_add_u64 v[210:211], v[210:211], 0, s[8:9]
	s_mov_b32 m0, s14
	ds_read_b128 v[178:181], v149 offset:49152
	ds_read_b128 v[182:185], v149 offset:50176
	ds_read_b128 v[186:189], v149 offset:51200
	ds_read_b128 v[190:193], v149 offset:52224
	ds_read_b128 v[194:197], v149 offset:53248
	ds_read_b128 v[198:201], v149 offset:54272
	ds_read_b128 v[202:205], v149 offset:55296
	ds_read_b128 v[206:209], v149 offset:56320
	global_load_lds_dwordx4 v[210:211], off
	s_add_i32 m0, s14, 0x2000
	s_add_u32 s14, s18, 0xb0080
	v_lshl_add_u64 v[210:211], v[212:213], 0, s[8:9]
	s_addc_u32 s15, s19, 0
	s_add_i32 s18, s41, s22
	global_load_lds_dwordx4 v[210:211], off
	v_lshl_add_u64 v[210:211], s[14:15], 0, v[130:131]
	s_mov_b32 m0, s18
	s_nop 0
	global_load_lds_dwordx4 v[210:211], off
	v_lshl_add_u64 v[210:211], s[14:15], 0, v[128:129]
	s_add_i32 m0, s18, 0x2000
	s_nop 0
	global_load_lds_dwordx4 v[210:211], off
	v_lshl_add_u64 v[210:211], v[214:215], 0, s[8:9]
	s_mov_b32 m0, s27
	s_nop 0
	global_load_lds_dwordx4 v[210:211], off
	v_lshl_add_u64 v[210:211], v[216:217], 0, s[8:9]
	s_mov_b32 m0, s28
	s_nop 0
	global_load_lds_dwordx4 v[210:211], off
	s_waitcnt vmcnt(8)
	s_waitcnt lgkmcnt(0)
	s_barrier
	s_waitcnt lgkmcnt(0)
	v_mfma_f32_16x16x32_bf16 v[60:63], v[142:145], v[178:181], v[60:63]
	v_mfma_f32_16x16x32_bf16 v[56:59], v[154:157], v[178:181], v[56:59]
	v_mfma_f32_16x16x32_bf16 v[44:47], v[142:145], v[186:189], v[44:47]
	v_mfma_f32_16x16x32_bf16 v[40:43], v[154:157], v[186:189], v[40:43]
	v_mfma_f32_16x16x32_bf16 v[28:31], v[142:145], v[194:197], v[28:31]
	v_mfma_f32_16x16x32_bf16 v[24:27], v[154:157], v[194:197], v[24:27]
	v_mfma_f32_16x16x32_bf16 v[12:15], v[142:145], v[202:205], v[12:15]
	v_mfma_f32_16x16x32_bf16 v[8:11], v[154:157], v[202:205], v[8:11]
	v_mfma_f32_16x16x32_bf16 v[60:63], v[150:153], v[182:185], v[60:63]
	v_mfma_f32_16x16x32_bf16 v[56:59], v[158:161], v[182:185], v[56:59]
	v_mfma_f32_16x16x32_bf16 v[44:47], v[150:153], v[190:193], v[44:47]
	v_mfma_f32_16x16x32_bf16 v[40:43], v[158:161], v[190:193], v[40:43]
	v_mfma_f32_16x16x32_bf16 v[28:31], v[150:153], v[198:201], v[28:31]
	v_mfma_f32_16x16x32_bf16 v[24:27], v[158:161], v[198:201], v[24:27]
	v_mfma_f32_16x16x32_bf16 v[12:15], v[150:153], v[206:209], v[12:15]
	v_mfma_f32_16x16x32_bf16 v[8:11], v[158:161], v[206:209], v[8:11]
	v_mfma_f32_16x16x32_bf16 v[52:55], v[162:165], v[178:181], v[52:55]
	v_mfma_f32_16x16x32_bf16 v[48:51], v[170:173], v[178:181], v[48:51]
	v_mfma_f32_16x16x32_bf16 v[36:39], v[162:165], v[186:189], v[36:39]
	v_mfma_f32_16x16x32_bf16 v[32:35], v[170:173], v[186:189], v[32:35]
	v_mfma_f32_16x16x32_bf16 v[20:23], v[162:165], v[194:197], v[20:23]
	v_mfma_f32_16x16x32_bf16 v[16:19], v[170:173], v[194:197], v[16:19]
	v_mfma_f32_16x16x32_bf16 v[4:7], v[162:165], v[202:205], v[4:7]
	v_mfma_f32_16x16x32_bf16 v[0:3], v[170:173], v[202:205], v[0:3]
	v_mfma_f32_16x16x32_bf16 v[52:55], v[166:169], v[182:185], v[52:55]
	v_mfma_f32_16x16x32_bf16 v[48:51], v[174:177], v[182:185], v[48:51]
	v_mfma_f32_16x16x32_bf16 v[36:39], v[166:169], v[190:193], v[36:39]
	v_mfma_f32_16x16x32_bf16 v[32:35], v[174:177], v[190:193], v[32:35]
	v_mfma_f32_16x16x32_bf16 v[20:23], v[166:169], v[198:201], v[20:23]
	v_mfma_f32_16x16x32_bf16 v[16:19], v[174:177], v[198:201], v[16:19]
	v_mfma_f32_16x16x32_bf16 v[4:7], v[166:169], v[206:209], v[4:7]
	v_mfma_f32_16x16x32_bf16 v[0:3], v[174:177], v[206:209], v[0:3]
	s_barrier
	s_add_i32 s39, s39, 2
	s_add_u32 s37, s37, 0x100
	s_addc_u32 s38, s38, 0
	s_cmp_gt_u32 s39, 41
	s_mov_b64 s[14:15], s[16:17]
	s_cbranch_scc1 .Lpeel_x5
